# p0_mod skinny tasks: dwordx2 rolling prefetch (64 loads in flight, pair-lane transposition), same MFMA order
# baseline (speedup 1.0000x reference)
.LBB0_47:
	s_waitcnt vmcnt(0)
	s_mov_b32 vcc_lo, 0xaaaaaaaa
	s_mov_b32 vcc_hi, 0xaaaaaaaa
	v_readfirstlane_b32 s100, v60
	v_readfirstlane_b32 s101, v61
	v_and_b32_e32 v24, 1, v227
	v_lshrrev_b32_e32 v25, 4, v227
	v_lshl_add_u32 v25, v25, 3, v24
	v_mul_u32_u24_e32 v65, 0x6000, v25
	v_and_b32_e32 v24, 14, v227
	v_lshl_add_u32 v65, v24, 2, v65
	s_sub_u32 s100, s100, 0x56a000
	s_subb_u32 s101, s101, 0
	v_add_u32_e32 v122, v64, v1
	v_add_u32_e32 v123, 0x11220, v122
	v_add_u32_e32 v28, v63, v1
	v_add_u32_e32 v29, 0x11220, v28
	ds_read_b128 v[198:201], v122
	ds_read_b128 v[202:205], v123
	ds_read_b128 v[206:209], v122 offset:33024
	ds_read_b128 v[210:213], v123 offset:33024
	ds_read_b128 v[214:217], v28
	ds_read_b128 v[218:221], v29
	global_load_dwordx2 v[66:67], v65, s[100:101]
	s_add_u32 s100, s100, 0xc000
	s_addc_u32 s101, s101, 0
	global_load_dwordx2 v[68:69], v65, s[100:101]
	s_add_u32 s100, s100, 0xc000
	s_addc_u32 s101, s101, 0
	global_load_dwordx2 v[70:71], v65, s[100:101]
	s_add_u32 s100, s100, 0xc000
	s_addc_u32 s101, s101, 0
	global_load_dwordx2 v[72:73], v65, s[100:101]
	s_add_u32 s100, s100, 0x9c000
	s_addc_u32 s101, s101, 0
	global_load_dwordx2 v[74:75], v65, s[100:101]
	s_add_u32 s100, s100, 0xc000
	s_addc_u32 s101, s101, 0
	global_load_dwordx2 v[76:77], v65, s[100:101]
	s_add_u32 s100, s100, 0xc000
	s_addc_u32 s101, s101, 0
	global_load_dwordx2 v[78:79], v65, s[100:101]
	s_add_u32 s100, s100, 0xc000
	s_addc_u32 s101, s101, 0
	global_load_dwordx2 v[80:81], v65, s[100:101]
	s_add_u32 s100, s100, 0x9c000
	s_addc_u32 s101, s101, 0
	global_load_dwordx2 v[82:83], v65, s[100:101]
	s_add_u32 s100, s100, 0xc000
	s_addc_u32 s101, s101, 0
	global_load_dwordx2 v[84:85], v65, s[100:101]
	s_add_u32 s100, s100, 0xc000
	s_addc_u32 s101, s101, 0
	global_load_dwordx2 v[86:87], v65, s[100:101]
	s_add_u32 s100, s100, 0xc000
	s_addc_u32 s101, s101, 0
	global_load_dwordx2 v[88:89], v65, s[100:101]
	s_add_u32 s100, s100, 0x9c000
	s_addc_u32 s101, s101, 0
	global_load_dwordx2 v[90:91], v65, s[100:101]
	s_add_u32 s100, s100, 0xc000
	s_addc_u32 s101, s101, 0
	global_load_dwordx2 v[92:93], v65, s[100:101]
	s_add_u32 s100, s100, 0xc000
	s_addc_u32 s101, s101, 0
	global_load_dwordx2 v[94:95], v65, s[100:101]
	s_add_u32 s100, s100, 0xc000
	s_addc_u32 s101, s101, 0
	global_load_dwordx2 v[96:97], v65, s[100:101]
	s_add_u32 s100, s100, 0x9c000
	s_addc_u32 s101, s101, 0
	global_load_dwordx2 v[98:99], v65, s[100:101]
	s_add_u32 s100, s100, 0xc000
	s_addc_u32 s101, s101, 0
	global_load_dwordx2 v[100:101], v65, s[100:101]
	s_add_u32 s100, s100, 0xc000
	s_addc_u32 s101, s101, 0
	global_load_dwordx2 v[102:103], v65, s[100:101]
	s_add_u32 s100, s100, 0xc000
	s_addc_u32 s101, s101, 0
	global_load_dwordx2 v[104:105], v65, s[100:101]
	s_add_u32 s100, s100, 0x9c000
	s_addc_u32 s101, s101, 0
	global_load_dwordx2 v[106:107], v65, s[100:101]
	s_add_u32 s100, s100, 0xc000
	s_addc_u32 s101, s101, 0
	global_load_dwordx2 v[108:109], v65, s[100:101]
	s_add_u32 s100, s100, 0xc000
	s_addc_u32 s101, s101, 0
	global_load_dwordx2 v[110:111], v65, s[100:101]
	s_add_u32 s100, s100, 0xc000
	s_addc_u32 s101, s101, 0
	global_load_dwordx2 v[112:113], v65, s[100:101]
	s_add_u32 s100, s100, 0x9c000
	s_addc_u32 s101, s101, 0
	global_load_dwordx2 v[114:115], v65, s[100:101]
	s_add_u32 s100, s100, 0xc000
	s_addc_u32 s101, s101, 0
	global_load_dwordx2 v[116:117], v65, s[100:101]
	s_add_u32 s100, s100, 0xc000
	s_addc_u32 s101, s101, 0
	global_load_dwordx2 v[118:119], v65, s[100:101]
	s_add_u32 s100, s100, 0xc000
	s_addc_u32 s101, s101, 0
	global_load_dwordx2 v[120:121], v65, s[100:101]
	s_add_u32 s100, s100, 0x9c000
	s_addc_u32 s101, s101, 0
	global_load_dwordx2 v[126:127], v65, s[100:101]
	s_add_u32 s100, s100, 0xc000
	s_addc_u32 s101, s101, 0
	global_load_dwordx2 v[128:129], v65, s[100:101]
	s_add_u32 s100, s100, 0xc000
	s_addc_u32 s101, s101, 0
	global_load_dwordx2 v[130:131], v65, s[100:101]
	s_add_u32 s100, s100, 0xc000
	s_addc_u32 s101, s101, 0
	global_load_dwordx2 v[132:133], v65, s[100:101]
	s_add_u32 s100, s100, 0x9c000
	s_addc_u32 s101, s101, 0
	global_load_dwordx2 v[134:135], v65, s[100:101]
	s_add_u32 s100, s100, 0xc000
	s_addc_u32 s101, s101, 0
	global_load_dwordx2 v[136:137], v65, s[100:101]
	s_add_u32 s100, s100, 0xc000
	s_addc_u32 s101, s101, 0
	global_load_dwordx2 v[138:139], v65, s[100:101]
	s_add_u32 s100, s100, 0xc000
	s_addc_u32 s101, s101, 0
	global_load_dwordx2 v[140:141], v65, s[100:101]
	s_add_u32 s100, s100, 0x9c000
	s_addc_u32 s101, s101, 0
	global_load_dwordx2 v[142:143], v65, s[100:101]
	s_add_u32 s100, s100, 0xc000
	s_addc_u32 s101, s101, 0
	global_load_dwordx2 v[144:145], v65, s[100:101]
	s_add_u32 s100, s100, 0xc000
	s_addc_u32 s101, s101, 0
	global_load_dwordx2 v[146:147], v65, s[100:101]
	s_add_u32 s100, s100, 0xc000
	s_addc_u32 s101, s101, 0
	global_load_dwordx2 v[148:149], v65, s[100:101]
	s_add_u32 s100, s100, 0x9c000
	s_addc_u32 s101, s101, 0
	global_load_dwordx2 v[150:151], v65, s[100:101]
	s_add_u32 s100, s100, 0xc000
	s_addc_u32 s101, s101, 0
	global_load_dwordx2 v[152:153], v65, s[100:101]
	s_add_u32 s100, s100, 0xc000
	s_addc_u32 s101, s101, 0
	global_load_dwordx2 v[154:155], v65, s[100:101]
	s_add_u32 s100, s100, 0xc000
	s_addc_u32 s101, s101, 0
	global_load_dwordx2 v[156:157], v65, s[100:101]
	s_add_u32 s100, s100, 0x9c000
	s_addc_u32 s101, s101, 0
	global_load_dwordx2 v[158:159], v65, s[100:101]
	s_add_u32 s100, s100, 0xc000
	s_addc_u32 s101, s101, 0
	global_load_dwordx2 v[160:161], v65, s[100:101]
	s_add_u32 s100, s100, 0xc000
	s_addc_u32 s101, s101, 0
	global_load_dwordx2 v[162:163], v65, s[100:101]
	s_add_u32 s100, s100, 0xc000
	s_addc_u32 s101, s101, 0
	global_load_dwordx2 v[164:165], v65, s[100:101]
	s_add_u32 s100, s100, 0x9c000
	s_addc_u32 s101, s101, 0
	global_load_dwordx2 v[166:167], v65, s[100:101]
	s_add_u32 s100, s100, 0xc000
	s_addc_u32 s101, s101, 0
	global_load_dwordx2 v[168:169], v65, s[100:101]
	s_add_u32 s100, s100, 0xc000
	s_addc_u32 s101, s101, 0
	global_load_dwordx2 v[170:171], v65, s[100:101]
	s_add_u32 s100, s100, 0xc000
	s_addc_u32 s101, s101, 0
	global_load_dwordx2 v[172:173], v65, s[100:101]
	s_add_u32 s100, s100, 0x9c000
	s_addc_u32 s101, s101, 0
	global_load_dwordx2 v[174:175], v65, s[100:101]
	s_add_u32 s100, s100, 0xc000
	s_addc_u32 s101, s101, 0
	global_load_dwordx2 v[176:177], v65, s[100:101]
	s_add_u32 s100, s100, 0xc000
	s_addc_u32 s101, s101, 0
	global_load_dwordx2 v[178:179], v65, s[100:101]
	s_add_u32 s100, s100, 0xc000
	s_addc_u32 s101, s101, 0
	global_load_dwordx2 v[180:181], v65, s[100:101]
	s_add_u32 s100, s100, 0x9c000
	s_addc_u32 s101, s101, 0
	global_load_dwordx2 v[182:183], v65, s[100:101]
	s_add_u32 s100, s100, 0xc000
	s_addc_u32 s101, s101, 0
	global_load_dwordx2 v[184:185], v65, s[100:101]
	s_add_u32 s100, s100, 0xc000
	s_addc_u32 s101, s101, 0
	global_load_dwordx2 v[186:187], v65, s[100:101]
	s_add_u32 s100, s100, 0xc000
	s_addc_u32 s101, s101, 0
	global_load_dwordx2 v[188:189], v65, s[100:101]
	s_add_u32 s100, s100, 0x9c000
	s_addc_u32 s101, s101, 0
	global_load_dwordx2 v[190:191], v65, s[100:101]
	s_add_u32 s100, s100, 0xc000
	s_addc_u32 s101, s101, 0
	global_load_dwordx2 v[192:193], v65, s[100:101]
	s_add_u32 s100, s100, 0xc000
	s_addc_u32 s101, s101, 0
	global_load_dwordx2 v[194:195], v65, s[100:101]
	s_add_u32 s100, s100, 0xc000
	s_addc_u32 s101, s101, 0
	global_load_dwordx2 v[196:197], v65, s[100:101]
	s_add_u32 s100, s100, 0x9c000
	s_addc_u32 s101, s101, 0
	s_waitcnt vmcnt(60)
	v_cndmask_b32_e64 v24, v67, v66, vcc
	v_cndmask_b32_e64 v25, v69, v68, vcc
	v_cndmask_b32_e64 v26, v71, v70, vcc
	v_cndmask_b32_e64 v27, v73, v72, vcc
	v_mov_b32_dpp v222, v24 quad_perm:[1,0,3,2] row_mask:0xf bank_mask:0xf
	v_mov_b32_dpp v223, v25 quad_perm:[1,0,3,2] row_mask:0xf bank_mask:0xf
	v_mov_b32_dpp v224, v26 quad_perm:[1,0,3,2] row_mask:0xf bank_mask:0xf
	v_mov_b32_dpp v225, v27 quad_perm:[1,0,3,2] row_mask:0xf bank_mask:0xf
	v_cndmask_b32_e64 v66, v66, v222, vcc
	v_cndmask_b32_e64 v67, v222, v67, vcc
	v_cndmask_b32_e64 v68, v68, v223, vcc
	v_cndmask_b32_e64 v69, v223, v69, vcc
	v_cndmask_b32_e64 v70, v70, v224, vcc
	v_cndmask_b32_e64 v71, v224, v71, vcc
	v_cndmask_b32_e64 v72, v72, v225, vcc
	v_cndmask_b32_e64 v73, v225, v73, vcc
	v_cvt_pk_bf16_f32 v14, v66, v67
	v_cvt_pk_bf16_f32 v15, v68, v69
	v_cvt_pk_bf16_f32 v16, v70, v71
	v_cvt_pk_bf16_f32 v17, v72, v73
	v_lshlrev_b32_e32 v22, 16, v14
	v_and_b32_e32 v23, 0xffff0000, v14
	v_sub_f32_e32 v66, v66, v22
	v_sub_f32_e32 v67, v67, v23
	v_cvt_pk_bf16_f32 v18, v66, v67
	v_lshlrev_b32_e32 v22, 16, v15
	v_and_b32_e32 v23, 0xffff0000, v15
	v_sub_f32_e32 v68, v68, v22
	v_sub_f32_e32 v69, v69, v23
	v_cvt_pk_bf16_f32 v19, v68, v69
	v_lshlrev_b32_e32 v22, 16, v16
	v_and_b32_e32 v23, 0xffff0000, v16
	v_sub_f32_e32 v70, v70, v22
	v_sub_f32_e32 v71, v71, v23
	v_cvt_pk_bf16_f32 v20, v70, v71
	v_lshlrev_b32_e32 v22, 16, v17
	v_and_b32_e32 v23, 0xffff0000, v17
	v_sub_f32_e32 v72, v72, v22
	v_sub_f32_e32 v73, v73, v23
	v_cvt_pk_bf16_f32 v21, v72, v73
	global_load_dwordx2 v[66:67], v65, s[100:101]
	s_add_u32 s100, s100, 0xc000
	s_addc_u32 s101, s101, 0
	global_load_dwordx2 v[68:69], v65, s[100:101]
	s_add_u32 s100, s100, 0xc000
	s_addc_u32 s101, s101, 0
	global_load_dwordx2 v[70:71], v65, s[100:101]
	s_add_u32 s100, s100, 0xc000
	s_addc_u32 s101, s101, 0
	global_load_dwordx2 v[72:73], v65, s[100:101]
	s_add_u32 s100, s100, 0x9c000
	s_addc_u32 s101, s101, 0
	s_waitcnt lgkmcnt(0)
	v_mfma_f32_16x16x32_bf16 v[10:13], v[198:201], v[14:17], v[10:13]
	v_mfma_f32_16x16x32_bf16 v[6:9], v[206:209], v[14:17], v[6:9]
	v_mfma_f32_16x16x32_bf16 v[2:5], v[214:217], v[14:17], v[2:5]
	v_mfma_f32_16x16x32_bf16 v[10:13], v[198:201], v[18:21], v[10:13]
	ds_read_b128 v[198:201], v122 offset:64
	v_mfma_f32_16x16x32_bf16 v[6:9], v[206:209], v[18:21], v[6:9]
	ds_read_b128 v[206:209], v122 offset:33088
	v_mfma_f32_16x16x32_bf16 v[2:5], v[214:217], v[18:21], v[2:5]
	ds_read_b128 v[214:217], v28 offset:64
	v_mfma_f32_16x16x32_bf16 v[10:13], v[202:205], v[14:17], v[10:13]
	ds_read_b128 v[202:205], v123 offset:64
	v_mfma_f32_16x16x32_bf16 v[6:9], v[210:213], v[14:17], v[6:9]
	ds_read_b128 v[210:213], v123 offset:33088
	v_mfma_f32_16x16x32_bf16 v[2:5], v[218:221], v[14:17], v[2:5]
	ds_read_b128 v[218:221], v29 offset:64
	s_waitcnt vmcnt(60)
	v_cndmask_b32_e64 v24, v75, v74, vcc
	v_cndmask_b32_e64 v25, v77, v76, vcc
	v_cndmask_b32_e64 v26, v79, v78, vcc
	v_cndmask_b32_e64 v27, v81, v80, vcc
	v_mov_b32_dpp v222, v24 quad_perm:[1,0,3,2] row_mask:0xf bank_mask:0xf
	v_mov_b32_dpp v223, v25 quad_perm:[1,0,3,2] row_mask:0xf bank_mask:0xf
	v_mov_b32_dpp v224, v26 quad_perm:[1,0,3,2] row_mask:0xf bank_mask:0xf
	v_mov_b32_dpp v225, v27 quad_perm:[1,0,3,2] row_mask:0xf bank_mask:0xf
	v_cndmask_b32_e64 v74, v74, v222, vcc
	v_cndmask_b32_e64 v75, v222, v75, vcc
	v_cndmask_b32_e64 v76, v76, v223, vcc
	v_cndmask_b32_e64 v77, v223, v77, vcc
	v_cndmask_b32_e64 v78, v78, v224, vcc
	v_cndmask_b32_e64 v79, v224, v79, vcc
	v_cndmask_b32_e64 v80, v80, v225, vcc
	v_cndmask_b32_e64 v81, v225, v81, vcc
	v_cvt_pk_bf16_f32 v14, v74, v75
	v_cvt_pk_bf16_f32 v15, v76, v77
	v_cvt_pk_bf16_f32 v16, v78, v79
	v_cvt_pk_bf16_f32 v17, v80, v81
	v_lshlrev_b32_e32 v22, 16, v14
	v_and_b32_e32 v23, 0xffff0000, v14
	v_sub_f32_e32 v74, v74, v22
	v_sub_f32_e32 v75, v75, v23
	v_cvt_pk_bf16_f32 v18, v74, v75
	v_lshlrev_b32_e32 v22, 16, v15
	v_and_b32_e32 v23, 0xffff0000, v15
	v_sub_f32_e32 v76, v76, v22
	v_sub_f32_e32 v77, v77, v23
	v_cvt_pk_bf16_f32 v19, v76, v77
	v_lshlrev_b32_e32 v22, 16, v16
	v_and_b32_e32 v23, 0xffff0000, v16
	v_sub_f32_e32 v78, v78, v22
	v_sub_f32_e32 v79, v79, v23
	v_cvt_pk_bf16_f32 v20, v78, v79
	v_lshlrev_b32_e32 v22, 16, v17
	v_and_b32_e32 v23, 0xffff0000, v17
	v_sub_f32_e32 v80, v80, v22
	v_sub_f32_e32 v81, v81, v23
	v_cvt_pk_bf16_f32 v21, v80, v81
	global_load_dwordx2 v[74:75], v65, s[100:101]
	s_add_u32 s100, s100, 0xc000
	s_addc_u32 s101, s101, 0
	global_load_dwordx2 v[76:77], v65, s[100:101]
	s_add_u32 s100, s100, 0xc000
	s_addc_u32 s101, s101, 0
	global_load_dwordx2 v[78:79], v65, s[100:101]
	s_add_u32 s100, s100, 0xc000
	s_addc_u32 s101, s101, 0
	global_load_dwordx2 v[80:81], v65, s[100:101]
	s_add_u32 s100, s100, 0x9c000
	s_addc_u32 s101, s101, 0
	s_waitcnt lgkmcnt(0)
	v_mfma_f32_16x16x32_bf16 v[10:13], v[198:201], v[14:17], v[10:13]
	v_mfma_f32_16x16x32_bf16 v[6:9], v[206:209], v[14:17], v[6:9]
	v_mfma_f32_16x16x32_bf16 v[2:5], v[214:217], v[14:17], v[2:5]
	v_mfma_f32_16x16x32_bf16 v[10:13], v[198:201], v[18:21], v[10:13]
	ds_read_b128 v[198:201], v122 offset:128
	v_mfma_f32_16x16x32_bf16 v[6:9], v[206:209], v[18:21], v[6:9]
	ds_read_b128 v[206:209], v122 offset:33152
	v_mfma_f32_16x16x32_bf16 v[2:5], v[214:217], v[18:21], v[2:5]
	ds_read_b128 v[214:217], v28 offset:128
	v_mfma_f32_16x16x32_bf16 v[10:13], v[202:205], v[14:17], v[10:13]
	ds_read_b128 v[202:205], v123 offset:128
	v_mfma_f32_16x16x32_bf16 v[6:9], v[210:213], v[14:17], v[6:9]
	ds_read_b128 v[210:213], v123 offset:33152
	v_mfma_f32_16x16x32_bf16 v[2:5], v[218:221], v[14:17], v[2:5]
	ds_read_b128 v[218:221], v29 offset:128
	s_waitcnt vmcnt(60)
	v_cndmask_b32_e64 v24, v83, v82, vcc
	v_cndmask_b32_e64 v25, v85, v84, vcc
	v_cndmask_b32_e64 v26, v87, v86, vcc
	v_cndmask_b32_e64 v27, v89, v88, vcc
	v_mov_b32_dpp v222, v24 quad_perm:[1,0,3,2] row_mask:0xf bank_mask:0xf
	v_mov_b32_dpp v223, v25 quad_perm:[1,0,3,2] row_mask:0xf bank_mask:0xf
	v_mov_b32_dpp v224, v26 quad_perm:[1,0,3,2] row_mask:0xf bank_mask:0xf
	v_mov_b32_dpp v225, v27 quad_perm:[1,0,3,2] row_mask:0xf bank_mask:0xf
	v_cndmask_b32_e64 v82, v82, v222, vcc
	v_cndmask_b32_e64 v83, v222, v83, vcc
	v_cndmask_b32_e64 v84, v84, v223, vcc
	v_cndmask_b32_e64 v85, v223, v85, vcc
	v_cndmask_b32_e64 v86, v86, v224, vcc
	v_cndmask_b32_e64 v87, v224, v87, vcc
	v_cndmask_b32_e64 v88, v88, v225, vcc
	v_cndmask_b32_e64 v89, v225, v89, vcc
	v_cvt_pk_bf16_f32 v14, v82, v83
	v_cvt_pk_bf16_f32 v15, v84, v85
	v_cvt_pk_bf16_f32 v16, v86, v87
	v_cvt_pk_bf16_f32 v17, v88, v89
	v_lshlrev_b32_e32 v22, 16, v14
	v_and_b32_e32 v23, 0xffff0000, v14
	v_sub_f32_e32 v82, v82, v22
	v_sub_f32_e32 v83, v83, v23
	v_cvt_pk_bf16_f32 v18, v82, v83
	v_lshlrev_b32_e32 v22, 16, v15
	v_and_b32_e32 v23, 0xffff0000, v15
	v_sub_f32_e32 v84, v84, v22
	v_sub_f32_e32 v85, v85, v23
	v_cvt_pk_bf16_f32 v19, v84, v85
	v_lshlrev_b32_e32 v22, 16, v16
	v_and_b32_e32 v23, 0xffff0000, v16
	v_sub_f32_e32 v86, v86, v22
	v_sub_f32_e32 v87, v87, v23
	v_cvt_pk_bf16_f32 v20, v86, v87
	v_lshlrev_b32_e32 v22, 16, v17
	v_and_b32_e32 v23, 0xffff0000, v17
	v_sub_f32_e32 v88, v88, v22
	v_sub_f32_e32 v89, v89, v23
	v_cvt_pk_bf16_f32 v21, v88, v89
	global_load_dwordx2 v[82:83], v65, s[100:101]
	s_add_u32 s100, s100, 0xc000
	s_addc_u32 s101, s101, 0
	global_load_dwordx2 v[84:85], v65, s[100:101]
	s_add_u32 s100, s100, 0xc000
	s_addc_u32 s101, s101, 0
	global_load_dwordx2 v[86:87], v65, s[100:101]
	s_add_u32 s100, s100, 0xc000
	s_addc_u32 s101, s101, 0
	global_load_dwordx2 v[88:89], v65, s[100:101]
	s_add_u32 s100, s100, 0x9c000
	s_addc_u32 s101, s101, 0
	s_waitcnt lgkmcnt(0)
	v_mfma_f32_16x16x32_bf16 v[10:13], v[198:201], v[14:17], v[10:13]
	v_mfma_f32_16x16x32_bf16 v[6:9], v[206:209], v[14:17], v[6:9]
	v_mfma_f32_16x16x32_bf16 v[2:5], v[214:217], v[14:17], v[2:5]
	v_mfma_f32_16x16x32_bf16 v[10:13], v[198:201], v[18:21], v[10:13]
	ds_read_b128 v[198:201], v122 offset:192
	v_mfma_f32_16x16x32_bf16 v[6:9], v[206:209], v[18:21], v[6:9]
	ds_read_b128 v[206:209], v122 offset:33216
	v_mfma_f32_16x16x32_bf16 v[2:5], v[214:217], v[18:21], v[2:5]
	ds_read_b128 v[214:217], v28 offset:192
	v_mfma_f32_16x16x32_bf16 v[10:13], v[202:205], v[14:17], v[10:13]
	ds_read_b128 v[202:205], v123 offset:192
	v_mfma_f32_16x16x32_bf16 v[6:9], v[210:213], v[14:17], v[6:9]
	ds_read_b128 v[210:213], v123 offset:33216
	v_mfma_f32_16x16x32_bf16 v[2:5], v[218:221], v[14:17], v[2:5]
	ds_read_b128 v[218:221], v29 offset:192
	s_waitcnt vmcnt(60)
	v_cndmask_b32_e64 v24, v91, v90, vcc
	v_cndmask_b32_e64 v25, v93, v92, vcc
	v_cndmask_b32_e64 v26, v95, v94, vcc
	v_cndmask_b32_e64 v27, v97, v96, vcc
	v_mov_b32_dpp v222, v24 quad_perm:[1,0,3,2] row_mask:0xf bank_mask:0xf
	v_mov_b32_dpp v223, v25 quad_perm:[1,0,3,2] row_mask:0xf bank_mask:0xf
	v_mov_b32_dpp v224, v26 quad_perm:[1,0,3,2] row_mask:0xf bank_mask:0xf
	v_mov_b32_dpp v225, v27 quad_perm:[1,0,3,2] row_mask:0xf bank_mask:0xf
	v_cndmask_b32_e64 v90, v90, v222, vcc
	v_cndmask_b32_e64 v91, v222, v91, vcc
	v_cndmask_b32_e64 v92, v92, v223, vcc
	v_cndmask_b32_e64 v93, v223, v93, vcc
	v_cndmask_b32_e64 v94, v94, v224, vcc
	v_cndmask_b32_e64 v95, v224, v95, vcc
	v_cndmask_b32_e64 v96, v96, v225, vcc
	v_cndmask_b32_e64 v97, v225, v97, vcc
	v_cvt_pk_bf16_f32 v14, v90, v91
	v_cvt_pk_bf16_f32 v15, v92, v93
	v_cvt_pk_bf16_f32 v16, v94, v95
	v_cvt_pk_bf16_f32 v17, v96, v97
	v_lshlrev_b32_e32 v22, 16, v14
	v_and_b32_e32 v23, 0xffff0000, v14
	v_sub_f32_e32 v90, v90, v22
	v_sub_f32_e32 v91, v91, v23
	v_cvt_pk_bf16_f32 v18, v90, v91
	v_lshlrev_b32_e32 v22, 16, v15
	v_and_b32_e32 v23, 0xffff0000, v15
	v_sub_f32_e32 v92, v92, v22
	v_sub_f32_e32 v93, v93, v23
	v_cvt_pk_bf16_f32 v19, v92, v93
	v_lshlrev_b32_e32 v22, 16, v16
	v_and_b32_e32 v23, 0xffff0000, v16
	v_sub_f32_e32 v94, v94, v22
	v_sub_f32_e32 v95, v95, v23
	v_cvt_pk_bf16_f32 v20, v94, v95
	v_lshlrev_b32_e32 v22, 16, v17
	v_and_b32_e32 v23, 0xffff0000, v17
	v_sub_f32_e32 v96, v96, v22
	v_sub_f32_e32 v97, v97, v23
	v_cvt_pk_bf16_f32 v21, v96, v97
	global_load_dwordx2 v[90:91], v65, s[100:101]
	s_add_u32 s100, s100, 0xc000
	s_addc_u32 s101, s101, 0
	global_load_dwordx2 v[92:93], v65, s[100:101]
	s_add_u32 s100, s100, 0xc000
	s_addc_u32 s101, s101, 0
	global_load_dwordx2 v[94:95], v65, s[100:101]
	s_add_u32 s100, s100, 0xc000
	s_addc_u32 s101, s101, 0
	global_load_dwordx2 v[96:97], v65, s[100:101]
	s_add_u32 s100, s100, 0x9c000
	s_addc_u32 s101, s101, 0
	s_waitcnt lgkmcnt(0)
	v_mfma_f32_16x16x32_bf16 v[10:13], v[198:201], v[14:17], v[10:13]
	v_mfma_f32_16x16x32_bf16 v[6:9], v[206:209], v[14:17], v[6:9]
	v_mfma_f32_16x16x32_bf16 v[2:5], v[214:217], v[14:17], v[2:5]
	v_mfma_f32_16x16x32_bf16 v[10:13], v[198:201], v[18:21], v[10:13]
	ds_read_b128 v[198:201], v122 offset:256
	v_mfma_f32_16x16x32_bf16 v[6:9], v[206:209], v[18:21], v[6:9]
	ds_read_b128 v[206:209], v122 offset:33280
	v_mfma_f32_16x16x32_bf16 v[2:5], v[214:217], v[18:21], v[2:5]
	ds_read_b128 v[214:217], v28 offset:256
	v_mfma_f32_16x16x32_bf16 v[10:13], v[202:205], v[14:17], v[10:13]
	ds_read_b128 v[202:205], v123 offset:256
	v_mfma_f32_16x16x32_bf16 v[6:9], v[210:213], v[14:17], v[6:9]
	ds_read_b128 v[210:213], v123 offset:33280
	v_mfma_f32_16x16x32_bf16 v[2:5], v[218:221], v[14:17], v[2:5]
	ds_read_b128 v[218:221], v29 offset:256
	s_waitcnt vmcnt(60)
	v_cndmask_b32_e64 v24, v99, v98, vcc
	v_cndmask_b32_e64 v25, v101, v100, vcc
	v_cndmask_b32_e64 v26, v103, v102, vcc
	v_cndmask_b32_e64 v27, v105, v104, vcc
	v_mov_b32_dpp v222, v24 quad_perm:[1,0,3,2] row_mask:0xf bank_mask:0xf
	v_mov_b32_dpp v223, v25 quad_perm:[1,0,3,2] row_mask:0xf bank_mask:0xf
	v_mov_b32_dpp v224, v26 quad_perm:[1,0,3,2] row_mask:0xf bank_mask:0xf
	v_mov_b32_dpp v225, v27 quad_perm:[1,0,3,2] row_mask:0xf bank_mask:0xf
	v_cndmask_b32_e64 v98, v98, v222, vcc
	v_cndmask_b32_e64 v99, v222, v99, vcc
	v_cndmask_b32_e64 v100, v100, v223, vcc
	v_cndmask_b32_e64 v101, v223, v101, vcc
	v_cndmask_b32_e64 v102, v102, v224, vcc
	v_cndmask_b32_e64 v103, v224, v103, vcc
	v_cndmask_b32_e64 v104, v104, v225, vcc
	v_cndmask_b32_e64 v105, v225, v105, vcc
	v_cvt_pk_bf16_f32 v14, v98, v99
	v_cvt_pk_bf16_f32 v15, v100, v101
	v_cvt_pk_bf16_f32 v16, v102, v103
	v_cvt_pk_bf16_f32 v17, v104, v105
	v_lshlrev_b32_e32 v22, 16, v14
	v_and_b32_e32 v23, 0xffff0000, v14
	v_sub_f32_e32 v98, v98, v22
	v_sub_f32_e32 v99, v99, v23
	v_cvt_pk_bf16_f32 v18, v98, v99
	v_lshlrev_b32_e32 v22, 16, v15
	v_and_b32_e32 v23, 0xffff0000, v15
	v_sub_f32_e32 v100, v100, v22
	v_sub_f32_e32 v101, v101, v23
	v_cvt_pk_bf16_f32 v19, v100, v101
	v_lshlrev_b32_e32 v22, 16, v16
	v_and_b32_e32 v23, 0xffff0000, v16
	v_sub_f32_e32 v102, v102, v22
	v_sub_f32_e32 v103, v103, v23
	v_cvt_pk_bf16_f32 v20, v102, v103
	v_lshlrev_b32_e32 v22, 16, v17
	v_and_b32_e32 v23, 0xffff0000, v17
	v_sub_f32_e32 v104, v104, v22
	v_sub_f32_e32 v105, v105, v23
	v_cvt_pk_bf16_f32 v21, v104, v105
	global_load_dwordx2 v[98:99], v65, s[100:101]
	s_add_u32 s100, s100, 0xc000
	s_addc_u32 s101, s101, 0
	global_load_dwordx2 v[100:101], v65, s[100:101]
	s_add_u32 s100, s100, 0xc000
	s_addc_u32 s101, s101, 0
	global_load_dwordx2 v[102:103], v65, s[100:101]
	s_add_u32 s100, s100, 0xc000
	s_addc_u32 s101, s101, 0
	global_load_dwordx2 v[104:105], v65, s[100:101]
	s_add_u32 s100, s100, 0x9c000
	s_addc_u32 s101, s101, 0
	s_waitcnt lgkmcnt(0)
	v_mfma_f32_16x16x32_bf16 v[10:13], v[198:201], v[14:17], v[10:13]
	v_mfma_f32_16x16x32_bf16 v[6:9], v[206:209], v[14:17], v[6:9]
	v_mfma_f32_16x16x32_bf16 v[2:5], v[214:217], v[14:17], v[2:5]
	v_mfma_f32_16x16x32_bf16 v[10:13], v[198:201], v[18:21], v[10:13]
	ds_read_b128 v[198:201], v122 offset:320
	v_mfma_f32_16x16x32_bf16 v[6:9], v[206:209], v[18:21], v[6:9]
	ds_read_b128 v[206:209], v122 offset:33344
	v_mfma_f32_16x16x32_bf16 v[2:5], v[214:217], v[18:21], v[2:5]
	ds_read_b128 v[214:217], v28 offset:320
	v_mfma_f32_16x16x32_bf16 v[10:13], v[202:205], v[14:17], v[10:13]
	ds_read_b128 v[202:205], v123 offset:320
	v_mfma_f32_16x16x32_bf16 v[6:9], v[210:213], v[14:17], v[6:9]
	ds_read_b128 v[210:213], v123 offset:33344
	v_mfma_f32_16x16x32_bf16 v[2:5], v[218:221], v[14:17], v[2:5]
	ds_read_b128 v[218:221], v29 offset:320
	s_waitcnt vmcnt(60)
	v_cndmask_b32_e64 v24, v107, v106, vcc
	v_cndmask_b32_e64 v25, v109, v108, vcc
	v_cndmask_b32_e64 v26, v111, v110, vcc
	v_cndmask_b32_e64 v27, v113, v112, vcc
	v_mov_b32_dpp v222, v24 quad_perm:[1,0,3,2] row_mask:0xf bank_mask:0xf
	v_mov_b32_dpp v223, v25 quad_perm:[1,0,3,2] row_mask:0xf bank_mask:0xf
	v_mov_b32_dpp v224, v26 quad_perm:[1,0,3,2] row_mask:0xf bank_mask:0xf
	v_mov_b32_dpp v225, v27 quad_perm:[1,0,3,2] row_mask:0xf bank_mask:0xf
	v_cndmask_b32_e64 v106, v106, v222, vcc
	v_cndmask_b32_e64 v107, v222, v107, vcc
	v_cndmask_b32_e64 v108, v108, v223, vcc
	v_cndmask_b32_e64 v109, v223, v109, vcc
	v_cndmask_b32_e64 v110, v110, v224, vcc
	v_cndmask_b32_e64 v111, v224, v111, vcc
	v_cndmask_b32_e64 v112, v112, v225, vcc
	v_cndmask_b32_e64 v113, v225, v113, vcc
	v_cvt_pk_bf16_f32 v14, v106, v107
	v_cvt_pk_bf16_f32 v15, v108, v109
	v_cvt_pk_bf16_f32 v16, v110, v111
	v_cvt_pk_bf16_f32 v17, v112, v113
	v_lshlrev_b32_e32 v22, 16, v14
	v_and_b32_e32 v23, 0xffff0000, v14
	v_sub_f32_e32 v106, v106, v22
	v_sub_f32_e32 v107, v107, v23
	v_cvt_pk_bf16_f32 v18, v106, v107
	v_lshlrev_b32_e32 v22, 16, v15
	v_and_b32_e32 v23, 0xffff0000, v15
	v_sub_f32_e32 v108, v108, v22
	v_sub_f32_e32 v109, v109, v23
	v_cvt_pk_bf16_f32 v19, v108, v109
	v_lshlrev_b32_e32 v22, 16, v16
	v_and_b32_e32 v23, 0xffff0000, v16
	v_sub_f32_e32 v110, v110, v22
	v_sub_f32_e32 v111, v111, v23
	v_cvt_pk_bf16_f32 v20, v110, v111
	v_lshlrev_b32_e32 v22, 16, v17
	v_and_b32_e32 v23, 0xffff0000, v17
	v_sub_f32_e32 v112, v112, v22
	v_sub_f32_e32 v113, v113, v23
	v_cvt_pk_bf16_f32 v21, v112, v113
	global_load_dwordx2 v[106:107], v65, s[100:101]
	s_add_u32 s100, s100, 0xc000
	s_addc_u32 s101, s101, 0
	global_load_dwordx2 v[108:109], v65, s[100:101]
	s_add_u32 s100, s100, 0xc000
	s_addc_u32 s101, s101, 0
	global_load_dwordx2 v[110:111], v65, s[100:101]
	s_add_u32 s100, s100, 0xc000
	s_addc_u32 s101, s101, 0
	global_load_dwordx2 v[112:113], v65, s[100:101]
	s_add_u32 s100, s100, 0x9c000
	s_addc_u32 s101, s101, 0
	s_waitcnt lgkmcnt(0)
	v_mfma_f32_16x16x32_bf16 v[10:13], v[198:201], v[14:17], v[10:13]
	v_mfma_f32_16x16x32_bf16 v[6:9], v[206:209], v[14:17], v[6:9]
	v_mfma_f32_16x16x32_bf16 v[2:5], v[214:217], v[14:17], v[2:5]
	v_mfma_f32_16x16x32_bf16 v[10:13], v[198:201], v[18:21], v[10:13]
	ds_read_b128 v[198:201], v122 offset:384
	v_mfma_f32_16x16x32_bf16 v[6:9], v[206:209], v[18:21], v[6:9]
	ds_read_b128 v[206:209], v122 offset:33408
	v_mfma_f32_16x16x32_bf16 v[2:5], v[214:217], v[18:21], v[2:5]
	ds_read_b128 v[214:217], v28 offset:384
	v_mfma_f32_16x16x32_bf16 v[10:13], v[202:205], v[14:17], v[10:13]
	ds_read_b128 v[202:205], v123 offset:384
	v_mfma_f32_16x16x32_bf16 v[6:9], v[210:213], v[14:17], v[6:9]
	ds_read_b128 v[210:213], v123 offset:33408
	v_mfma_f32_16x16x32_bf16 v[2:5], v[218:221], v[14:17], v[2:5]
	ds_read_b128 v[218:221], v29 offset:384
	s_waitcnt vmcnt(60)
	v_cndmask_b32_e64 v24, v115, v114, vcc
	v_cndmask_b32_e64 v25, v117, v116, vcc
	v_cndmask_b32_e64 v26, v119, v118, vcc
	v_cndmask_b32_e64 v27, v121, v120, vcc
	v_mov_b32_dpp v222, v24 quad_perm:[1,0,3,2] row_mask:0xf bank_mask:0xf
	v_mov_b32_dpp v223, v25 quad_perm:[1,0,3,2] row_mask:0xf bank_mask:0xf
	v_mov_b32_dpp v224, v26 quad_perm:[1,0,3,2] row_mask:0xf bank_mask:0xf
	v_mov_b32_dpp v225, v27 quad_perm:[1,0,3,2] row_mask:0xf bank_mask:0xf
	v_cndmask_b32_e64 v114, v114, v222, vcc
	v_cndmask_b32_e64 v115, v222, v115, vcc
	v_cndmask_b32_e64 v116, v116, v223, vcc
	v_cndmask_b32_e64 v117, v223, v117, vcc
	v_cndmask_b32_e64 v118, v118, v224, vcc
	v_cndmask_b32_e64 v119, v224, v119, vcc
	v_cndmask_b32_e64 v120, v120, v225, vcc
	v_cndmask_b32_e64 v121, v225, v121, vcc
	v_cvt_pk_bf16_f32 v14, v114, v115
	v_cvt_pk_bf16_f32 v15, v116, v117
	v_cvt_pk_bf16_f32 v16, v118, v119
	v_cvt_pk_bf16_f32 v17, v120, v121
	v_lshlrev_b32_e32 v22, 16, v14
	v_and_b32_e32 v23, 0xffff0000, v14
	v_sub_f32_e32 v114, v114, v22
	v_sub_f32_e32 v115, v115, v23
	v_cvt_pk_bf16_f32 v18, v114, v115
	v_lshlrev_b32_e32 v22, 16, v15
	v_and_b32_e32 v23, 0xffff0000, v15
	v_sub_f32_e32 v116, v116, v22
	v_sub_f32_e32 v117, v117, v23
	v_cvt_pk_bf16_f32 v19, v116, v117
	v_lshlrev_b32_e32 v22, 16, v16
	v_and_b32_e32 v23, 0xffff0000, v16
	v_sub_f32_e32 v118, v118, v22
	v_sub_f32_e32 v119, v119, v23
	v_cvt_pk_bf16_f32 v20, v118, v119
	v_lshlrev_b32_e32 v22, 16, v17
	v_and_b32_e32 v23, 0xffff0000, v17
	v_sub_f32_e32 v120, v120, v22
	v_sub_f32_e32 v121, v121, v23
	v_cvt_pk_bf16_f32 v21, v120, v121
	global_load_dwordx2 v[114:115], v65, s[100:101]
	s_add_u32 s100, s100, 0xc000
	s_addc_u32 s101, s101, 0
	global_load_dwordx2 v[116:117], v65, s[100:101]
	s_add_u32 s100, s100, 0xc000
	s_addc_u32 s101, s101, 0
	global_load_dwordx2 v[118:119], v65, s[100:101]
	s_add_u32 s100, s100, 0xc000
	s_addc_u32 s101, s101, 0
	global_load_dwordx2 v[120:121], v65, s[100:101]
	s_add_u32 s100, s100, 0x9c000
	s_addc_u32 s101, s101, 0
	s_waitcnt lgkmcnt(0)
	v_mfma_f32_16x16x32_bf16 v[10:13], v[198:201], v[14:17], v[10:13]
	v_mfma_f32_16x16x32_bf16 v[6:9], v[206:209], v[14:17], v[6:9]
	v_mfma_f32_16x16x32_bf16 v[2:5], v[214:217], v[14:17], v[2:5]
	v_mfma_f32_16x16x32_bf16 v[10:13], v[198:201], v[18:21], v[10:13]
	ds_read_b128 v[198:201], v122 offset:448
	v_mfma_f32_16x16x32_bf16 v[6:9], v[206:209], v[18:21], v[6:9]
	ds_read_b128 v[206:209], v122 offset:33472
	v_mfma_f32_16x16x32_bf16 v[2:5], v[214:217], v[18:21], v[2:5]
	ds_read_b128 v[214:217], v28 offset:448
	v_mfma_f32_16x16x32_bf16 v[10:13], v[202:205], v[14:17], v[10:13]
	ds_read_b128 v[202:205], v123 offset:448
	v_mfma_f32_16x16x32_bf16 v[6:9], v[210:213], v[14:17], v[6:9]
	ds_read_b128 v[210:213], v123 offset:33472
	v_mfma_f32_16x16x32_bf16 v[2:5], v[218:221], v[14:17], v[2:5]
	ds_read_b128 v[218:221], v29 offset:448
	s_waitcnt vmcnt(60)
	v_cndmask_b32_e64 v24, v127, v126, vcc
	v_cndmask_b32_e64 v25, v129, v128, vcc
	v_cndmask_b32_e64 v26, v131, v130, vcc
	v_cndmask_b32_e64 v27, v133, v132, vcc
	v_mov_b32_dpp v222, v24 quad_perm:[1,0,3,2] row_mask:0xf bank_mask:0xf
	v_mov_b32_dpp v223, v25 quad_perm:[1,0,3,2] row_mask:0xf bank_mask:0xf
	v_mov_b32_dpp v224, v26 quad_perm:[1,0,3,2] row_mask:0xf bank_mask:0xf
	v_mov_b32_dpp v225, v27 quad_perm:[1,0,3,2] row_mask:0xf bank_mask:0xf
	v_cndmask_b32_e64 v126, v126, v222, vcc
	v_cndmask_b32_e64 v127, v222, v127, vcc
	v_cndmask_b32_e64 v128, v128, v223, vcc
	v_cndmask_b32_e64 v129, v223, v129, vcc
	v_cndmask_b32_e64 v130, v130, v224, vcc
	v_cndmask_b32_e64 v131, v224, v131, vcc
	v_cndmask_b32_e64 v132, v132, v225, vcc
	v_cndmask_b32_e64 v133, v225, v133, vcc
	v_cvt_pk_bf16_f32 v14, v126, v127
	v_cvt_pk_bf16_f32 v15, v128, v129
	v_cvt_pk_bf16_f32 v16, v130, v131
	v_cvt_pk_bf16_f32 v17, v132, v133
	v_lshlrev_b32_e32 v22, 16, v14
	v_and_b32_e32 v23, 0xffff0000, v14
	v_sub_f32_e32 v126, v126, v22
	v_sub_f32_e32 v127, v127, v23
	v_cvt_pk_bf16_f32 v18, v126, v127
	v_lshlrev_b32_e32 v22, 16, v15
	v_and_b32_e32 v23, 0xffff0000, v15
	v_sub_f32_e32 v128, v128, v22
	v_sub_f32_e32 v129, v129, v23
	v_cvt_pk_bf16_f32 v19, v128, v129
	v_lshlrev_b32_e32 v22, 16, v16
	v_and_b32_e32 v23, 0xffff0000, v16
	v_sub_f32_e32 v130, v130, v22
	v_sub_f32_e32 v131, v131, v23
	v_cvt_pk_bf16_f32 v20, v130, v131
	v_lshlrev_b32_e32 v22, 16, v17
	v_and_b32_e32 v23, 0xffff0000, v17
	v_sub_f32_e32 v132, v132, v22
	v_sub_f32_e32 v133, v133, v23
	v_cvt_pk_bf16_f32 v21, v132, v133
	global_load_dwordx2 v[126:127], v65, s[100:101]
	s_add_u32 s100, s100, 0xc000
	s_addc_u32 s101, s101, 0
	global_load_dwordx2 v[128:129], v65, s[100:101]
	s_add_u32 s100, s100, 0xc000
	s_addc_u32 s101, s101, 0
	global_load_dwordx2 v[130:131], v65, s[100:101]
	s_add_u32 s100, s100, 0xc000
	s_addc_u32 s101, s101, 0
	global_load_dwordx2 v[132:133], v65, s[100:101]
	s_add_u32 s100, s100, 0x9c000
	s_addc_u32 s101, s101, 0
	s_waitcnt lgkmcnt(0)
	v_mfma_f32_16x16x32_bf16 v[10:13], v[198:201], v[14:17], v[10:13]
	v_mfma_f32_16x16x32_bf16 v[6:9], v[206:209], v[14:17], v[6:9]
	v_mfma_f32_16x16x32_bf16 v[2:5], v[214:217], v[14:17], v[2:5]
	v_mfma_f32_16x16x32_bf16 v[10:13], v[198:201], v[18:21], v[10:13]
	ds_read_b128 v[198:201], v122 offset:512
	v_mfma_f32_16x16x32_bf16 v[6:9], v[206:209], v[18:21], v[6:9]
	ds_read_b128 v[206:209], v122 offset:33536
	v_mfma_f32_16x16x32_bf16 v[2:5], v[214:217], v[18:21], v[2:5]
	ds_read_b128 v[214:217], v28 offset:512
	v_mfma_f32_16x16x32_bf16 v[10:13], v[202:205], v[14:17], v[10:13]
	ds_read_b128 v[202:205], v123 offset:512
	v_mfma_f32_16x16x32_bf16 v[6:9], v[210:213], v[14:17], v[6:9]
	ds_read_b128 v[210:213], v123 offset:33536
	v_mfma_f32_16x16x32_bf16 v[2:5], v[218:221], v[14:17], v[2:5]
	ds_read_b128 v[218:221], v29 offset:512
	s_waitcnt vmcnt(60)
	v_cndmask_b32_e64 v24, v135, v134, vcc
	v_cndmask_b32_e64 v25, v137, v136, vcc
	v_cndmask_b32_e64 v26, v139, v138, vcc
	v_cndmask_b32_e64 v27, v141, v140, vcc
	v_mov_b32_dpp v222, v24 quad_perm:[1,0,3,2] row_mask:0xf bank_mask:0xf
	v_mov_b32_dpp v223, v25 quad_perm:[1,0,3,2] row_mask:0xf bank_mask:0xf
	v_mov_b32_dpp v224, v26 quad_perm:[1,0,3,2] row_mask:0xf bank_mask:0xf
	v_mov_b32_dpp v225, v27 quad_perm:[1,0,3,2] row_mask:0xf bank_mask:0xf
	v_cndmask_b32_e64 v134, v134, v222, vcc
	v_cndmask_b32_e64 v135, v222, v135, vcc
	v_cndmask_b32_e64 v136, v136, v223, vcc
	v_cndmask_b32_e64 v137, v223, v137, vcc
	v_cndmask_b32_e64 v138, v138, v224, vcc
	v_cndmask_b32_e64 v139, v224, v139, vcc
	v_cndmask_b32_e64 v140, v140, v225, vcc
	v_cndmask_b32_e64 v141, v225, v141, vcc
	v_cvt_pk_bf16_f32 v14, v134, v135
	v_cvt_pk_bf16_f32 v15, v136, v137
	v_cvt_pk_bf16_f32 v16, v138, v139
	v_cvt_pk_bf16_f32 v17, v140, v141
	v_lshlrev_b32_e32 v22, 16, v14
	v_and_b32_e32 v23, 0xffff0000, v14
	v_sub_f32_e32 v134, v134, v22
	v_sub_f32_e32 v135, v135, v23
	v_cvt_pk_bf16_f32 v18, v134, v135
	v_lshlrev_b32_e32 v22, 16, v15
	v_and_b32_e32 v23, 0xffff0000, v15
	v_sub_f32_e32 v136, v136, v22
	v_sub_f32_e32 v137, v137, v23
	v_cvt_pk_bf16_f32 v19, v136, v137
	v_lshlrev_b32_e32 v22, 16, v16
	v_and_b32_e32 v23, 0xffff0000, v16
	v_sub_f32_e32 v138, v138, v22
	v_sub_f32_e32 v139, v139, v23
	v_cvt_pk_bf16_f32 v20, v138, v139
	v_lshlrev_b32_e32 v22, 16, v17
	v_and_b32_e32 v23, 0xffff0000, v17
	v_sub_f32_e32 v140, v140, v22
	v_sub_f32_e32 v141, v141, v23
	v_cvt_pk_bf16_f32 v21, v140, v141
	global_load_dwordx2 v[134:135], v65, s[100:101]
	s_add_u32 s100, s100, 0xc000
	s_addc_u32 s101, s101, 0
	global_load_dwordx2 v[136:137], v65, s[100:101]
	s_add_u32 s100, s100, 0xc000
	s_addc_u32 s101, s101, 0
	global_load_dwordx2 v[138:139], v65, s[100:101]
	s_add_u32 s100, s100, 0xc000
	s_addc_u32 s101, s101, 0
	global_load_dwordx2 v[140:141], v65, s[100:101]
	s_add_u32 s100, s100, 0x9c000
	s_addc_u32 s101, s101, 0
	s_waitcnt lgkmcnt(0)
	v_mfma_f32_16x16x32_bf16 v[10:13], v[198:201], v[14:17], v[10:13]
	v_mfma_f32_16x16x32_bf16 v[6:9], v[206:209], v[14:17], v[6:9]
	v_mfma_f32_16x16x32_bf16 v[2:5], v[214:217], v[14:17], v[2:5]
	v_mfma_f32_16x16x32_bf16 v[10:13], v[198:201], v[18:21], v[10:13]
	ds_read_b128 v[198:201], v122 offset:576
	v_mfma_f32_16x16x32_bf16 v[6:9], v[206:209], v[18:21], v[6:9]
	ds_read_b128 v[206:209], v122 offset:33600
	v_mfma_f32_16x16x32_bf16 v[2:5], v[214:217], v[18:21], v[2:5]
	ds_read_b128 v[214:217], v28 offset:576
	v_mfma_f32_16x16x32_bf16 v[10:13], v[202:205], v[14:17], v[10:13]
	ds_read_b128 v[202:205], v123 offset:576
	v_mfma_f32_16x16x32_bf16 v[6:9], v[210:213], v[14:17], v[6:9]
	ds_read_b128 v[210:213], v123 offset:33600
	v_mfma_f32_16x16x32_bf16 v[2:5], v[218:221], v[14:17], v[2:5]
	ds_read_b128 v[218:221], v29 offset:576
	s_waitcnt vmcnt(60)
	v_cndmask_b32_e64 v24, v143, v142, vcc
	v_cndmask_b32_e64 v25, v145, v144, vcc
	v_cndmask_b32_e64 v26, v147, v146, vcc
	v_cndmask_b32_e64 v27, v149, v148, vcc
	v_mov_b32_dpp v222, v24 quad_perm:[1,0,3,2] row_mask:0xf bank_mask:0xf
	v_mov_b32_dpp v223, v25 quad_perm:[1,0,3,2] row_mask:0xf bank_mask:0xf
	v_mov_b32_dpp v224, v26 quad_perm:[1,0,3,2] row_mask:0xf bank_mask:0xf
	v_mov_b32_dpp v225, v27 quad_perm:[1,0,3,2] row_mask:0xf bank_mask:0xf
	v_cndmask_b32_e64 v142, v142, v222, vcc
	v_cndmask_b32_e64 v143, v222, v143, vcc
	v_cndmask_b32_e64 v144, v144, v223, vcc
	v_cndmask_b32_e64 v145, v223, v145, vcc
	v_cndmask_b32_e64 v146, v146, v224, vcc
	v_cndmask_b32_e64 v147, v224, v147, vcc
	v_cndmask_b32_e64 v148, v148, v225, vcc
	v_cndmask_b32_e64 v149, v225, v149, vcc
	v_cvt_pk_bf16_f32 v14, v142, v143
	v_cvt_pk_bf16_f32 v15, v144, v145
	v_cvt_pk_bf16_f32 v16, v146, v147
	v_cvt_pk_bf16_f32 v17, v148, v149
	v_lshlrev_b32_e32 v22, 16, v14
	v_and_b32_e32 v23, 0xffff0000, v14
	v_sub_f32_e32 v142, v142, v22
	v_sub_f32_e32 v143, v143, v23
	v_cvt_pk_bf16_f32 v18, v142, v143
	v_lshlrev_b32_e32 v22, 16, v15
	v_and_b32_e32 v23, 0xffff0000, v15
	v_sub_f32_e32 v144, v144, v22
	v_sub_f32_e32 v145, v145, v23
	v_cvt_pk_bf16_f32 v19, v144, v145
	v_lshlrev_b32_e32 v22, 16, v16
	v_and_b32_e32 v23, 0xffff0000, v16
	v_sub_f32_e32 v146, v146, v22
	v_sub_f32_e32 v147, v147, v23
	v_cvt_pk_bf16_f32 v20, v146, v147
	v_lshlrev_b32_e32 v22, 16, v17
	v_and_b32_e32 v23, 0xffff0000, v17
	v_sub_f32_e32 v148, v148, v22
	v_sub_f32_e32 v149, v149, v23
	v_cvt_pk_bf16_f32 v21, v148, v149
	global_load_dwordx2 v[142:143], v65, s[100:101]
	s_add_u32 s100, s100, 0xc000
	s_addc_u32 s101, s101, 0
	global_load_dwordx2 v[144:145], v65, s[100:101]
	s_add_u32 s100, s100, 0xc000
	s_addc_u32 s101, s101, 0
	global_load_dwordx2 v[146:147], v65, s[100:101]
	s_add_u32 s100, s100, 0xc000
	s_addc_u32 s101, s101, 0
	global_load_dwordx2 v[148:149], v65, s[100:101]
	s_add_u32 s100, s100, 0x9c000
	s_addc_u32 s101, s101, 0
	s_waitcnt lgkmcnt(0)
	v_mfma_f32_16x16x32_bf16 v[10:13], v[198:201], v[14:17], v[10:13]
	v_mfma_f32_16x16x32_bf16 v[6:9], v[206:209], v[14:17], v[6:9]
	v_mfma_f32_16x16x32_bf16 v[2:5], v[214:217], v[14:17], v[2:5]
	v_mfma_f32_16x16x32_bf16 v[10:13], v[198:201], v[18:21], v[10:13]
	ds_read_b128 v[198:201], v122 offset:640
	v_mfma_f32_16x16x32_bf16 v[6:9], v[206:209], v[18:21], v[6:9]
	ds_read_b128 v[206:209], v122 offset:33664
	v_mfma_f32_16x16x32_bf16 v[2:5], v[214:217], v[18:21], v[2:5]
	ds_read_b128 v[214:217], v28 offset:640
	v_mfma_f32_16x16x32_bf16 v[10:13], v[202:205], v[14:17], v[10:13]
	ds_read_b128 v[202:205], v123 offset:640
	v_mfma_f32_16x16x32_bf16 v[6:9], v[210:213], v[14:17], v[6:9]
	ds_read_b128 v[210:213], v123 offset:33664
	v_mfma_f32_16x16x32_bf16 v[2:5], v[218:221], v[14:17], v[2:5]
	ds_read_b128 v[218:221], v29 offset:640
	s_waitcnt vmcnt(60)
	v_cndmask_b32_e64 v24, v151, v150, vcc
	v_cndmask_b32_e64 v25, v153, v152, vcc
	v_cndmask_b32_e64 v26, v155, v154, vcc
	v_cndmask_b32_e64 v27, v157, v156, vcc
	v_mov_b32_dpp v222, v24 quad_perm:[1,0,3,2] row_mask:0xf bank_mask:0xf
	v_mov_b32_dpp v223, v25 quad_perm:[1,0,3,2] row_mask:0xf bank_mask:0xf
	v_mov_b32_dpp v224, v26 quad_perm:[1,0,3,2] row_mask:0xf bank_mask:0xf
	v_mov_b32_dpp v225, v27 quad_perm:[1,0,3,2] row_mask:0xf bank_mask:0xf
	v_cndmask_b32_e64 v150, v150, v222, vcc
	v_cndmask_b32_e64 v151, v222, v151, vcc
	v_cndmask_b32_e64 v152, v152, v223, vcc
	v_cndmask_b32_e64 v153, v223, v153, vcc
	v_cndmask_b32_e64 v154, v154, v224, vcc
	v_cndmask_b32_e64 v155, v224, v155, vcc
	v_cndmask_b32_e64 v156, v156, v225, vcc
	v_cndmask_b32_e64 v157, v225, v157, vcc
	v_cvt_pk_bf16_f32 v14, v150, v151
	v_cvt_pk_bf16_f32 v15, v152, v153
	v_cvt_pk_bf16_f32 v16, v154, v155
	v_cvt_pk_bf16_f32 v17, v156, v157
	v_lshlrev_b32_e32 v22, 16, v14
	v_and_b32_e32 v23, 0xffff0000, v14
	v_sub_f32_e32 v150, v150, v22
	v_sub_f32_e32 v151, v151, v23
	v_cvt_pk_bf16_f32 v18, v150, v151
	v_lshlrev_b32_e32 v22, 16, v15
	v_and_b32_e32 v23, 0xffff0000, v15
	v_sub_f32_e32 v152, v152, v22
	v_sub_f32_e32 v153, v153, v23
	v_cvt_pk_bf16_f32 v19, v152, v153
	v_lshlrev_b32_e32 v22, 16, v16
	v_and_b32_e32 v23, 0xffff0000, v16
	v_sub_f32_e32 v154, v154, v22
	v_sub_f32_e32 v155, v155, v23
	v_cvt_pk_bf16_f32 v20, v154, v155
	v_lshlrev_b32_e32 v22, 16, v17
	v_and_b32_e32 v23, 0xffff0000, v17
	v_sub_f32_e32 v156, v156, v22
	v_sub_f32_e32 v157, v157, v23
	v_cvt_pk_bf16_f32 v21, v156, v157
	global_load_dwordx2 v[150:151], v65, s[100:101]
	s_add_u32 s100, s100, 0xc000
	s_addc_u32 s101, s101, 0
	global_load_dwordx2 v[152:153], v65, s[100:101]
	s_add_u32 s100, s100, 0xc000
	s_addc_u32 s101, s101, 0
	global_load_dwordx2 v[154:155], v65, s[100:101]
	s_add_u32 s100, s100, 0xc000
	s_addc_u32 s101, s101, 0
	global_load_dwordx2 v[156:157], v65, s[100:101]
	s_add_u32 s100, s100, 0x9c000
	s_addc_u32 s101, s101, 0
	s_waitcnt lgkmcnt(0)
	v_mfma_f32_16x16x32_bf16 v[10:13], v[198:201], v[14:17], v[10:13]
	v_mfma_f32_16x16x32_bf16 v[6:9], v[206:209], v[14:17], v[6:9]
	v_mfma_f32_16x16x32_bf16 v[2:5], v[214:217], v[14:17], v[2:5]
	v_mfma_f32_16x16x32_bf16 v[10:13], v[198:201], v[18:21], v[10:13]
	ds_read_b128 v[198:201], v122 offset:704
	v_mfma_f32_16x16x32_bf16 v[6:9], v[206:209], v[18:21], v[6:9]
	ds_read_b128 v[206:209], v122 offset:33728
	v_mfma_f32_16x16x32_bf16 v[2:5], v[214:217], v[18:21], v[2:5]
	ds_read_b128 v[214:217], v28 offset:704
	v_mfma_f32_16x16x32_bf16 v[10:13], v[202:205], v[14:17], v[10:13]
	ds_read_b128 v[202:205], v123 offset:704
	v_mfma_f32_16x16x32_bf16 v[6:9], v[210:213], v[14:17], v[6:9]
	ds_read_b128 v[210:213], v123 offset:33728
	v_mfma_f32_16x16x32_bf16 v[2:5], v[218:221], v[14:17], v[2:5]
	ds_read_b128 v[218:221], v29 offset:704
	s_waitcnt vmcnt(60)
	v_cndmask_b32_e64 v24, v159, v158, vcc
	v_cndmask_b32_e64 v25, v161, v160, vcc
	v_cndmask_b32_e64 v26, v163, v162, vcc
	v_cndmask_b32_e64 v27, v165, v164, vcc
	v_mov_b32_dpp v222, v24 quad_perm:[1,0,3,2] row_mask:0xf bank_mask:0xf
	v_mov_b32_dpp v223, v25 quad_perm:[1,0,3,2] row_mask:0xf bank_mask:0xf
	v_mov_b32_dpp v224, v26 quad_perm:[1,0,3,2] row_mask:0xf bank_mask:0xf
	v_mov_b32_dpp v225, v27 quad_perm:[1,0,3,2] row_mask:0xf bank_mask:0xf
	v_cndmask_b32_e64 v158, v158, v222, vcc
	v_cndmask_b32_e64 v159, v222, v159, vcc
	v_cndmask_b32_e64 v160, v160, v223, vcc
	v_cndmask_b32_e64 v161, v223, v161, vcc
	v_cndmask_b32_e64 v162, v162, v224, vcc
	v_cndmask_b32_e64 v163, v224, v163, vcc
	v_cndmask_b32_e64 v164, v164, v225, vcc
	v_cndmask_b32_e64 v165, v225, v165, vcc
	v_cvt_pk_bf16_f32 v14, v158, v159
	v_cvt_pk_bf16_f32 v15, v160, v161
	v_cvt_pk_bf16_f32 v16, v162, v163
	v_cvt_pk_bf16_f32 v17, v164, v165
	v_lshlrev_b32_e32 v22, 16, v14
	v_and_b32_e32 v23, 0xffff0000, v14
	v_sub_f32_e32 v158, v158, v22
	v_sub_f32_e32 v159, v159, v23
	v_cvt_pk_bf16_f32 v18, v158, v159
	v_lshlrev_b32_e32 v22, 16, v15
	v_and_b32_e32 v23, 0xffff0000, v15
	v_sub_f32_e32 v160, v160, v22
	v_sub_f32_e32 v161, v161, v23
	v_cvt_pk_bf16_f32 v19, v160, v161
	v_lshlrev_b32_e32 v22, 16, v16
	v_and_b32_e32 v23, 0xffff0000, v16
	v_sub_f32_e32 v162, v162, v22
	v_sub_f32_e32 v163, v163, v23
	v_cvt_pk_bf16_f32 v20, v162, v163
	v_lshlrev_b32_e32 v22, 16, v17
	v_and_b32_e32 v23, 0xffff0000, v17
	v_sub_f32_e32 v164, v164, v22
	v_sub_f32_e32 v165, v165, v23
	v_cvt_pk_bf16_f32 v21, v164, v165
	global_load_dwordx2 v[158:159], v65, s[100:101]
	s_add_u32 s100, s100, 0xc000
	s_addc_u32 s101, s101, 0
	global_load_dwordx2 v[160:161], v65, s[100:101]
	s_add_u32 s100, s100, 0xc000
	s_addc_u32 s101, s101, 0
	global_load_dwordx2 v[162:163], v65, s[100:101]
	s_add_u32 s100, s100, 0xc000
	s_addc_u32 s101, s101, 0
	global_load_dwordx2 v[164:165], v65, s[100:101]
	s_add_u32 s100, s100, 0x9c000
	s_addc_u32 s101, s101, 0
	s_waitcnt lgkmcnt(0)
	v_mfma_f32_16x16x32_bf16 v[10:13], v[198:201], v[14:17], v[10:13]
	v_mfma_f32_16x16x32_bf16 v[6:9], v[206:209], v[14:17], v[6:9]
	v_mfma_f32_16x16x32_bf16 v[2:5], v[214:217], v[14:17], v[2:5]
	v_mfma_f32_16x16x32_bf16 v[10:13], v[198:201], v[18:21], v[10:13]
	ds_read_b128 v[198:201], v122 offset:768
	v_mfma_f32_16x16x32_bf16 v[6:9], v[206:209], v[18:21], v[6:9]
	ds_read_b128 v[206:209], v122 offset:33792
	v_mfma_f32_16x16x32_bf16 v[2:5], v[214:217], v[18:21], v[2:5]
	ds_read_b128 v[214:217], v28 offset:768
	v_mfma_f32_16x16x32_bf16 v[10:13], v[202:205], v[14:17], v[10:13]
	ds_read_b128 v[202:205], v123 offset:768
	v_mfma_f32_16x16x32_bf16 v[6:9], v[210:213], v[14:17], v[6:9]
	ds_read_b128 v[210:213], v123 offset:33792
	v_mfma_f32_16x16x32_bf16 v[2:5], v[218:221], v[14:17], v[2:5]
	ds_read_b128 v[218:221], v29 offset:768
	s_waitcnt vmcnt(60)
	v_cndmask_b32_e64 v24, v167, v166, vcc
	v_cndmask_b32_e64 v25, v169, v168, vcc
	v_cndmask_b32_e64 v26, v171, v170, vcc
	v_cndmask_b32_e64 v27, v173, v172, vcc
	v_mov_b32_dpp v222, v24 quad_perm:[1,0,3,2] row_mask:0xf bank_mask:0xf
	v_mov_b32_dpp v223, v25 quad_perm:[1,0,3,2] row_mask:0xf bank_mask:0xf
	v_mov_b32_dpp v224, v26 quad_perm:[1,0,3,2] row_mask:0xf bank_mask:0xf
	v_mov_b32_dpp v225, v27 quad_perm:[1,0,3,2] row_mask:0xf bank_mask:0xf
	v_cndmask_b32_e64 v166, v166, v222, vcc
	v_cndmask_b32_e64 v167, v222, v167, vcc
	v_cndmask_b32_e64 v168, v168, v223, vcc
	v_cndmask_b32_e64 v169, v223, v169, vcc
	v_cndmask_b32_e64 v170, v170, v224, vcc
	v_cndmask_b32_e64 v171, v224, v171, vcc
	v_cndmask_b32_e64 v172, v172, v225, vcc
	v_cndmask_b32_e64 v173, v225, v173, vcc
	v_cvt_pk_bf16_f32 v14, v166, v167
	v_cvt_pk_bf16_f32 v15, v168, v169
	v_cvt_pk_bf16_f32 v16, v170, v171
	v_cvt_pk_bf16_f32 v17, v172, v173
	v_lshlrev_b32_e32 v22, 16, v14
	v_and_b32_e32 v23, 0xffff0000, v14
	v_sub_f32_e32 v166, v166, v22
	v_sub_f32_e32 v167, v167, v23
	v_cvt_pk_bf16_f32 v18, v166, v167
	v_lshlrev_b32_e32 v22, 16, v15
	v_and_b32_e32 v23, 0xffff0000, v15
	v_sub_f32_e32 v168, v168, v22
	v_sub_f32_e32 v169, v169, v23
	v_cvt_pk_bf16_f32 v19, v168, v169
	v_lshlrev_b32_e32 v22, 16, v16
	v_and_b32_e32 v23, 0xffff0000, v16
	v_sub_f32_e32 v170, v170, v22
	v_sub_f32_e32 v171, v171, v23
	v_cvt_pk_bf16_f32 v20, v170, v171
	v_lshlrev_b32_e32 v22, 16, v17
	v_and_b32_e32 v23, 0xffff0000, v17
	v_sub_f32_e32 v172, v172, v22
	v_sub_f32_e32 v173, v173, v23
	v_cvt_pk_bf16_f32 v21, v172, v173
	global_load_dwordx2 v[166:167], v65, s[100:101]
	s_add_u32 s100, s100, 0xc000
	s_addc_u32 s101, s101, 0
	global_load_dwordx2 v[168:169], v65, s[100:101]
	s_add_u32 s100, s100, 0xc000
	s_addc_u32 s101, s101, 0
	global_load_dwordx2 v[170:171], v65, s[100:101]
	s_add_u32 s100, s100, 0xc000
	s_addc_u32 s101, s101, 0
	global_load_dwordx2 v[172:173], v65, s[100:101]
	s_add_u32 s100, s100, 0x9c000
	s_addc_u32 s101, s101, 0
	s_waitcnt lgkmcnt(0)
	v_mfma_f32_16x16x32_bf16 v[10:13], v[198:201], v[14:17], v[10:13]
	v_mfma_f32_16x16x32_bf16 v[6:9], v[206:209], v[14:17], v[6:9]
	v_mfma_f32_16x16x32_bf16 v[2:5], v[214:217], v[14:17], v[2:5]
	v_mfma_f32_16x16x32_bf16 v[10:13], v[198:201], v[18:21], v[10:13]
	ds_read_b128 v[198:201], v122 offset:832
	v_mfma_f32_16x16x32_bf16 v[6:9], v[206:209], v[18:21], v[6:9]
	ds_read_b128 v[206:209], v122 offset:33856
	v_mfma_f32_16x16x32_bf16 v[2:5], v[214:217], v[18:21], v[2:5]
	ds_read_b128 v[214:217], v28 offset:832
	v_mfma_f32_16x16x32_bf16 v[10:13], v[202:205], v[14:17], v[10:13]
	ds_read_b128 v[202:205], v123 offset:832
	v_mfma_f32_16x16x32_bf16 v[6:9], v[210:213], v[14:17], v[6:9]
	ds_read_b128 v[210:213], v123 offset:33856
	v_mfma_f32_16x16x32_bf16 v[2:5], v[218:221], v[14:17], v[2:5]
	ds_read_b128 v[218:221], v29 offset:832
	s_waitcnt vmcnt(60)
	v_cndmask_b32_e64 v24, v175, v174, vcc
	v_cndmask_b32_e64 v25, v177, v176, vcc
	v_cndmask_b32_e64 v26, v179, v178, vcc
	v_cndmask_b32_e64 v27, v181, v180, vcc
	v_mov_b32_dpp v222, v24 quad_perm:[1,0,3,2] row_mask:0xf bank_mask:0xf
	v_mov_b32_dpp v223, v25 quad_perm:[1,0,3,2] row_mask:0xf bank_mask:0xf
	v_mov_b32_dpp v224, v26 quad_perm:[1,0,3,2] row_mask:0xf bank_mask:0xf
	v_mov_b32_dpp v225, v27 quad_perm:[1,0,3,2] row_mask:0xf bank_mask:0xf
	v_cndmask_b32_e64 v174, v174, v222, vcc
	v_cndmask_b32_e64 v175, v222, v175, vcc
	v_cndmask_b32_e64 v176, v176, v223, vcc
	v_cndmask_b32_e64 v177, v223, v177, vcc
	v_cndmask_b32_e64 v178, v178, v224, vcc
	v_cndmask_b32_e64 v179, v224, v179, vcc
	v_cndmask_b32_e64 v180, v180, v225, vcc
	v_cndmask_b32_e64 v181, v225, v181, vcc
	v_cvt_pk_bf16_f32 v14, v174, v175
	v_cvt_pk_bf16_f32 v15, v176, v177
	v_cvt_pk_bf16_f32 v16, v178, v179
	v_cvt_pk_bf16_f32 v17, v180, v181
	v_lshlrev_b32_e32 v22, 16, v14
	v_and_b32_e32 v23, 0xffff0000, v14
	v_sub_f32_e32 v174, v174, v22
	v_sub_f32_e32 v175, v175, v23
	v_cvt_pk_bf16_f32 v18, v174, v175
	v_lshlrev_b32_e32 v22, 16, v15
	v_and_b32_e32 v23, 0xffff0000, v15
	v_sub_f32_e32 v176, v176, v22
	v_sub_f32_e32 v177, v177, v23
	v_cvt_pk_bf16_f32 v19, v176, v177
	v_lshlrev_b32_e32 v22, 16, v16
	v_and_b32_e32 v23, 0xffff0000, v16
	v_sub_f32_e32 v178, v178, v22
	v_sub_f32_e32 v179, v179, v23
	v_cvt_pk_bf16_f32 v20, v178, v179
	v_lshlrev_b32_e32 v22, 16, v17
	v_and_b32_e32 v23, 0xffff0000, v17
	v_sub_f32_e32 v180, v180, v22
	v_sub_f32_e32 v181, v181, v23
	v_cvt_pk_bf16_f32 v21, v180, v181
	global_load_dwordx2 v[174:175], v65, s[100:101]
	s_add_u32 s100, s100, 0xc000
	s_addc_u32 s101, s101, 0
	global_load_dwordx2 v[176:177], v65, s[100:101]
	s_add_u32 s100, s100, 0xc000
	s_addc_u32 s101, s101, 0
	global_load_dwordx2 v[178:179], v65, s[100:101]
	s_add_u32 s100, s100, 0xc000
	s_addc_u32 s101, s101, 0
	global_load_dwordx2 v[180:181], v65, s[100:101]
	s_add_u32 s100, s100, 0x9c000
	s_addc_u32 s101, s101, 0
	s_waitcnt lgkmcnt(0)
	v_mfma_f32_16x16x32_bf16 v[10:13], v[198:201], v[14:17], v[10:13]
	v_mfma_f32_16x16x32_bf16 v[6:9], v[206:209], v[14:17], v[6:9]
	v_mfma_f32_16x16x32_bf16 v[2:5], v[214:217], v[14:17], v[2:5]
	v_mfma_f32_16x16x32_bf16 v[10:13], v[198:201], v[18:21], v[10:13]
	ds_read_b128 v[198:201], v122 offset:896
	v_mfma_f32_16x16x32_bf16 v[6:9], v[206:209], v[18:21], v[6:9]
	ds_read_b128 v[206:209], v122 offset:33920
	v_mfma_f32_16x16x32_bf16 v[2:5], v[214:217], v[18:21], v[2:5]
	ds_read_b128 v[214:217], v28 offset:896
	v_mfma_f32_16x16x32_bf16 v[10:13], v[202:205], v[14:17], v[10:13]
	ds_read_b128 v[202:205], v123 offset:896
	v_mfma_f32_16x16x32_bf16 v[6:9], v[210:213], v[14:17], v[6:9]
	ds_read_b128 v[210:213], v123 offset:33920
	v_mfma_f32_16x16x32_bf16 v[2:5], v[218:221], v[14:17], v[2:5]
	ds_read_b128 v[218:221], v29 offset:896
	s_waitcnt vmcnt(60)
	v_cndmask_b32_e64 v24, v183, v182, vcc
	v_cndmask_b32_e64 v25, v185, v184, vcc
	v_cndmask_b32_e64 v26, v187, v186, vcc
	v_cndmask_b32_e64 v27, v189, v188, vcc
	v_mov_b32_dpp v222, v24 quad_perm:[1,0,3,2] row_mask:0xf bank_mask:0xf
	v_mov_b32_dpp v223, v25 quad_perm:[1,0,3,2] row_mask:0xf bank_mask:0xf
	v_mov_b32_dpp v224, v26 quad_perm:[1,0,3,2] row_mask:0xf bank_mask:0xf
	v_mov_b32_dpp v225, v27 quad_perm:[1,0,3,2] row_mask:0xf bank_mask:0xf
	v_cndmask_b32_e64 v182, v182, v222, vcc
	v_cndmask_b32_e64 v183, v222, v183, vcc
	v_cndmask_b32_e64 v184, v184, v223, vcc
	v_cndmask_b32_e64 v185, v223, v185, vcc
	v_cndmask_b32_e64 v186, v186, v224, vcc
	v_cndmask_b32_e64 v187, v224, v187, vcc
	v_cndmask_b32_e64 v188, v188, v225, vcc
	v_cndmask_b32_e64 v189, v225, v189, vcc
	v_cvt_pk_bf16_f32 v14, v182, v183
	v_cvt_pk_bf16_f32 v15, v184, v185
	v_cvt_pk_bf16_f32 v16, v186, v187
	v_cvt_pk_bf16_f32 v17, v188, v189
	v_lshlrev_b32_e32 v22, 16, v14
	v_and_b32_e32 v23, 0xffff0000, v14
	v_sub_f32_e32 v182, v182, v22
	v_sub_f32_e32 v183, v183, v23
	v_cvt_pk_bf16_f32 v18, v182, v183
	v_lshlrev_b32_e32 v22, 16, v15
	v_and_b32_e32 v23, 0xffff0000, v15
	v_sub_f32_e32 v184, v184, v22
	v_sub_f32_e32 v185, v185, v23
	v_cvt_pk_bf16_f32 v19, v184, v185
	v_lshlrev_b32_e32 v22, 16, v16
	v_and_b32_e32 v23, 0xffff0000, v16
	v_sub_f32_e32 v186, v186, v22
	v_sub_f32_e32 v187, v187, v23
	v_cvt_pk_bf16_f32 v20, v186, v187
	v_lshlrev_b32_e32 v22, 16, v17
	v_and_b32_e32 v23, 0xffff0000, v17
	v_sub_f32_e32 v188, v188, v22
	v_sub_f32_e32 v189, v189, v23
	v_cvt_pk_bf16_f32 v21, v188, v189
	global_load_dwordx2 v[182:183], v65, s[100:101]
	s_add_u32 s100, s100, 0xc000
	s_addc_u32 s101, s101, 0
	global_load_dwordx2 v[184:185], v65, s[100:101]
	s_add_u32 s100, s100, 0xc000
	s_addc_u32 s101, s101, 0
	global_load_dwordx2 v[186:187], v65, s[100:101]
	s_add_u32 s100, s100, 0xc000
	s_addc_u32 s101, s101, 0
	global_load_dwordx2 v[188:189], v65, s[100:101]
	s_add_u32 s100, s100, 0x9c000
	s_addc_u32 s101, s101, 0
	s_waitcnt lgkmcnt(0)
	v_mfma_f32_16x16x32_bf16 v[10:13], v[198:201], v[14:17], v[10:13]
	v_mfma_f32_16x16x32_bf16 v[6:9], v[206:209], v[14:17], v[6:9]
	v_mfma_f32_16x16x32_bf16 v[2:5], v[214:217], v[14:17], v[2:5]
	v_mfma_f32_16x16x32_bf16 v[10:13], v[198:201], v[18:21], v[10:13]
	ds_read_b128 v[198:201], v122 offset:960
	v_mfma_f32_16x16x32_bf16 v[6:9], v[206:209], v[18:21], v[6:9]
	ds_read_b128 v[206:209], v122 offset:33984
	v_mfma_f32_16x16x32_bf16 v[2:5], v[214:217], v[18:21], v[2:5]
	ds_read_b128 v[214:217], v28 offset:960
	v_mfma_f32_16x16x32_bf16 v[10:13], v[202:205], v[14:17], v[10:13]
	ds_read_b128 v[202:205], v123 offset:960
	v_mfma_f32_16x16x32_bf16 v[6:9], v[210:213], v[14:17], v[6:9]
	ds_read_b128 v[210:213], v123 offset:33984
	v_mfma_f32_16x16x32_bf16 v[2:5], v[218:221], v[14:17], v[2:5]
	ds_read_b128 v[218:221], v29 offset:960
	s_waitcnt vmcnt(60)
	v_cndmask_b32_e64 v24, v191, v190, vcc
	v_cndmask_b32_e64 v25, v193, v192, vcc
	v_cndmask_b32_e64 v26, v195, v194, vcc
	v_cndmask_b32_e64 v27, v197, v196, vcc
	v_mov_b32_dpp v222, v24 quad_perm:[1,0,3,2] row_mask:0xf bank_mask:0xf
	v_mov_b32_dpp v223, v25 quad_perm:[1,0,3,2] row_mask:0xf bank_mask:0xf
	v_mov_b32_dpp v224, v26 quad_perm:[1,0,3,2] row_mask:0xf bank_mask:0xf
	v_mov_b32_dpp v225, v27 quad_perm:[1,0,3,2] row_mask:0xf bank_mask:0xf
	v_cndmask_b32_e64 v190, v190, v222, vcc
	v_cndmask_b32_e64 v191, v222, v191, vcc
	v_cndmask_b32_e64 v192, v192, v223, vcc
	v_cndmask_b32_e64 v193, v223, v193, vcc
	v_cndmask_b32_e64 v194, v194, v224, vcc
	v_cndmask_b32_e64 v195, v224, v195, vcc
	v_cndmask_b32_e64 v196, v196, v225, vcc
	v_cndmask_b32_e64 v197, v225, v197, vcc
	v_cvt_pk_bf16_f32 v14, v190, v191
	v_cvt_pk_bf16_f32 v15, v192, v193
	v_cvt_pk_bf16_f32 v16, v194, v195
	v_cvt_pk_bf16_f32 v17, v196, v197
	v_lshlrev_b32_e32 v22, 16, v14
	v_and_b32_e32 v23, 0xffff0000, v14
	v_sub_f32_e32 v190, v190, v22
	v_sub_f32_e32 v191, v191, v23
	v_cvt_pk_bf16_f32 v18, v190, v191
	v_lshlrev_b32_e32 v22, 16, v15
	v_and_b32_e32 v23, 0xffff0000, v15
	v_sub_f32_e32 v192, v192, v22
	v_sub_f32_e32 v193, v193, v23
	v_cvt_pk_bf16_f32 v19, v192, v193
	v_lshlrev_b32_e32 v22, 16, v16
	v_and_b32_e32 v23, 0xffff0000, v16
	v_sub_f32_e32 v194, v194, v22
	v_sub_f32_e32 v195, v195, v23
	v_cvt_pk_bf16_f32 v20, v194, v195
	v_lshlrev_b32_e32 v22, 16, v17
	v_and_b32_e32 v23, 0xffff0000, v17
	v_sub_f32_e32 v196, v196, v22
	v_sub_f32_e32 v197, v197, v23
	v_cvt_pk_bf16_f32 v21, v196, v197
	global_load_dwordx2 v[190:191], v65, s[100:101]
	s_add_u32 s100, s100, 0xc000
	s_addc_u32 s101, s101, 0
	global_load_dwordx2 v[192:193], v65, s[100:101]
	s_add_u32 s100, s100, 0xc000
	s_addc_u32 s101, s101, 0
	global_load_dwordx2 v[194:195], v65, s[100:101]
	s_add_u32 s100, s100, 0xc000
	s_addc_u32 s101, s101, 0
	global_load_dwordx2 v[196:197], v65, s[100:101]
	s_add_u32 s100, s100, 0x9c000
	s_addc_u32 s101, s101, 0
	s_waitcnt lgkmcnt(0)
	v_mfma_f32_16x16x32_bf16 v[10:13], v[198:201], v[14:17], v[10:13]
	v_mfma_f32_16x16x32_bf16 v[6:9], v[206:209], v[14:17], v[6:9]
	v_mfma_f32_16x16x32_bf16 v[2:5], v[214:217], v[14:17], v[2:5]
	v_mfma_f32_16x16x32_bf16 v[10:13], v[198:201], v[18:21], v[10:13]
	ds_read_b128 v[198:201], v122 offset:1024
	v_mfma_f32_16x16x32_bf16 v[6:9], v[206:209], v[18:21], v[6:9]
	ds_read_b128 v[206:209], v122 offset:34048
	v_mfma_f32_16x16x32_bf16 v[2:5], v[214:217], v[18:21], v[2:5]
	ds_read_b128 v[214:217], v28 offset:1024
	v_mfma_f32_16x16x32_bf16 v[10:13], v[202:205], v[14:17], v[10:13]
	ds_read_b128 v[202:205], v123 offset:1024
	v_mfma_f32_16x16x32_bf16 v[6:9], v[210:213], v[14:17], v[6:9]
	ds_read_b128 v[210:213], v123 offset:34048
	v_mfma_f32_16x16x32_bf16 v[2:5], v[218:221], v[14:17], v[2:5]
	ds_read_b128 v[218:221], v29 offset:1024
	s_waitcnt vmcnt(60)
	v_cndmask_b32_e64 v24, v67, v66, vcc
	v_cndmask_b32_e64 v25, v69, v68, vcc
	v_cndmask_b32_e64 v26, v71, v70, vcc
	v_cndmask_b32_e64 v27, v73, v72, vcc
	v_mov_b32_dpp v222, v24 quad_perm:[1,0,3,2] row_mask:0xf bank_mask:0xf
	v_mov_b32_dpp v223, v25 quad_perm:[1,0,3,2] row_mask:0xf bank_mask:0xf
	v_mov_b32_dpp v224, v26 quad_perm:[1,0,3,2] row_mask:0xf bank_mask:0xf
	v_mov_b32_dpp v225, v27 quad_perm:[1,0,3,2] row_mask:0xf bank_mask:0xf
	v_cndmask_b32_e64 v66, v66, v222, vcc
	v_cndmask_b32_e64 v67, v222, v67, vcc
	v_cndmask_b32_e64 v68, v68, v223, vcc
	v_cndmask_b32_e64 v69, v223, v69, vcc
	v_cndmask_b32_e64 v70, v70, v224, vcc
	v_cndmask_b32_e64 v71, v224, v71, vcc
	v_cndmask_b32_e64 v72, v72, v225, vcc
	v_cndmask_b32_e64 v73, v225, v73, vcc
	v_cvt_pk_bf16_f32 v14, v66, v67
	v_cvt_pk_bf16_f32 v15, v68, v69
	v_cvt_pk_bf16_f32 v16, v70, v71
	v_cvt_pk_bf16_f32 v17, v72, v73
	v_lshlrev_b32_e32 v22, 16, v14
	v_and_b32_e32 v23, 0xffff0000, v14
	v_sub_f32_e32 v66, v66, v22
	v_sub_f32_e32 v67, v67, v23
	v_cvt_pk_bf16_f32 v18, v66, v67
	v_lshlrev_b32_e32 v22, 16, v15
	v_and_b32_e32 v23, 0xffff0000, v15
	v_sub_f32_e32 v68, v68, v22
	v_sub_f32_e32 v69, v69, v23
	v_cvt_pk_bf16_f32 v19, v68, v69
	v_lshlrev_b32_e32 v22, 16, v16
	v_and_b32_e32 v23, 0xffff0000, v16
	v_sub_f32_e32 v70, v70, v22
	v_sub_f32_e32 v71, v71, v23
	v_cvt_pk_bf16_f32 v20, v70, v71
	v_lshlrev_b32_e32 v22, 16, v17
	v_and_b32_e32 v23, 0xffff0000, v17
	v_sub_f32_e32 v72, v72, v22
	v_sub_f32_e32 v73, v73, v23
	v_cvt_pk_bf16_f32 v21, v72, v73
	s_waitcnt lgkmcnt(0)
	v_mfma_f32_16x16x32_bf16 v[10:13], v[198:201], v[14:17], v[10:13]
	v_mfma_f32_16x16x32_bf16 v[6:9], v[206:209], v[14:17], v[6:9]
	v_mfma_f32_16x16x32_bf16 v[2:5], v[214:217], v[14:17], v[2:5]
	v_mfma_f32_16x16x32_bf16 v[10:13], v[198:201], v[18:21], v[10:13]
	ds_read_b128 v[198:201], v122 offset:1088
	v_mfma_f32_16x16x32_bf16 v[6:9], v[206:209], v[18:21], v[6:9]
	ds_read_b128 v[206:209], v122 offset:34112
	v_mfma_f32_16x16x32_bf16 v[2:5], v[214:217], v[18:21], v[2:5]
	ds_read_b128 v[214:217], v28 offset:1088
	v_mfma_f32_16x16x32_bf16 v[10:13], v[202:205], v[14:17], v[10:13]
	ds_read_b128 v[202:205], v123 offset:1088
	v_mfma_f32_16x16x32_bf16 v[6:9], v[210:213], v[14:17], v[6:9]
	ds_read_b128 v[210:213], v123 offset:34112
	v_mfma_f32_16x16x32_bf16 v[2:5], v[218:221], v[14:17], v[2:5]
	ds_read_b128 v[218:221], v29 offset:1088
	s_waitcnt vmcnt(56)
	v_cndmask_b32_e64 v24, v75, v74, vcc
	v_cndmask_b32_e64 v25, v77, v76, vcc
	v_cndmask_b32_e64 v26, v79, v78, vcc
	v_cndmask_b32_e64 v27, v81, v80, vcc
	v_mov_b32_dpp v222, v24 quad_perm:[1,0,3,2] row_mask:0xf bank_mask:0xf
	v_mov_b32_dpp v223, v25 quad_perm:[1,0,3,2] row_mask:0xf bank_mask:0xf
	v_mov_b32_dpp v224, v26 quad_perm:[1,0,3,2] row_mask:0xf bank_mask:0xf
	v_mov_b32_dpp v225, v27 quad_perm:[1,0,3,2] row_mask:0xf bank_mask:0xf
	v_cndmask_b32_e64 v74, v74, v222, vcc
	v_cndmask_b32_e64 v75, v222, v75, vcc
	v_cndmask_b32_e64 v76, v76, v223, vcc
	v_cndmask_b32_e64 v77, v223, v77, vcc
	v_cndmask_b32_e64 v78, v78, v224, vcc
	v_cndmask_b32_e64 v79, v224, v79, vcc
	v_cndmask_b32_e64 v80, v80, v225, vcc
	v_cndmask_b32_e64 v81, v225, v81, vcc
	v_cvt_pk_bf16_f32 v14, v74, v75
	v_cvt_pk_bf16_f32 v15, v76, v77
	v_cvt_pk_bf16_f32 v16, v78, v79
	v_cvt_pk_bf16_f32 v17, v80, v81
	v_lshlrev_b32_e32 v22, 16, v14
	v_and_b32_e32 v23, 0xffff0000, v14
	v_sub_f32_e32 v74, v74, v22
	v_sub_f32_e32 v75, v75, v23
	v_cvt_pk_bf16_f32 v18, v74, v75
	v_lshlrev_b32_e32 v22, 16, v15
	v_and_b32_e32 v23, 0xffff0000, v15
	v_sub_f32_e32 v76, v76, v22
	v_sub_f32_e32 v77, v77, v23
	v_cvt_pk_bf16_f32 v19, v76, v77
	v_lshlrev_b32_e32 v22, 16, v16
	v_and_b32_e32 v23, 0xffff0000, v16
	v_sub_f32_e32 v78, v78, v22
	v_sub_f32_e32 v79, v79, v23
	v_cvt_pk_bf16_f32 v20, v78, v79
	v_lshlrev_b32_e32 v22, 16, v17
	v_and_b32_e32 v23, 0xffff0000, v17
	v_sub_f32_e32 v80, v80, v22
	v_sub_f32_e32 v81, v81, v23
	v_cvt_pk_bf16_f32 v21, v80, v81
	s_waitcnt lgkmcnt(0)
	v_mfma_f32_16x16x32_bf16 v[10:13], v[198:201], v[14:17], v[10:13]
	v_mfma_f32_16x16x32_bf16 v[6:9], v[206:209], v[14:17], v[6:9]
	v_mfma_f32_16x16x32_bf16 v[2:5], v[214:217], v[14:17], v[2:5]
	v_mfma_f32_16x16x32_bf16 v[10:13], v[198:201], v[18:21], v[10:13]
	ds_read_b128 v[198:201], v122 offset:1152
	v_mfma_f32_16x16x32_bf16 v[6:9], v[206:209], v[18:21], v[6:9]
	ds_read_b128 v[206:209], v122 offset:34176
	v_mfma_f32_16x16x32_bf16 v[2:5], v[214:217], v[18:21], v[2:5]
	ds_read_b128 v[214:217], v28 offset:1152
	v_mfma_f32_16x16x32_bf16 v[10:13], v[202:205], v[14:17], v[10:13]
	ds_read_b128 v[202:205], v123 offset:1152
	v_mfma_f32_16x16x32_bf16 v[6:9], v[210:213], v[14:17], v[6:9]
	ds_read_b128 v[210:213], v123 offset:34176
	v_mfma_f32_16x16x32_bf16 v[2:5], v[218:221], v[14:17], v[2:5]
	ds_read_b128 v[218:221], v29 offset:1152
	s_waitcnt vmcnt(52)
	v_cndmask_b32_e64 v24, v83, v82, vcc
	v_cndmask_b32_e64 v25, v85, v84, vcc
	v_cndmask_b32_e64 v26, v87, v86, vcc
	v_cndmask_b32_e64 v27, v89, v88, vcc
	v_mov_b32_dpp v222, v24 quad_perm:[1,0,3,2] row_mask:0xf bank_mask:0xf
	v_mov_b32_dpp v223, v25 quad_perm:[1,0,3,2] row_mask:0xf bank_mask:0xf
	v_mov_b32_dpp v224, v26 quad_perm:[1,0,3,2] row_mask:0xf bank_mask:0xf
	v_mov_b32_dpp v225, v27 quad_perm:[1,0,3,2] row_mask:0xf bank_mask:0xf
	v_cndmask_b32_e64 v82, v82, v222, vcc
	v_cndmask_b32_e64 v83, v222, v83, vcc
	v_cndmask_b32_e64 v84, v84, v223, vcc
	v_cndmask_b32_e64 v85, v223, v85, vcc
	v_cndmask_b32_e64 v86, v86, v224, vcc
	v_cndmask_b32_e64 v87, v224, v87, vcc
	v_cndmask_b32_e64 v88, v88, v225, vcc
	v_cndmask_b32_e64 v89, v225, v89, vcc
	v_cvt_pk_bf16_f32 v14, v82, v83
	v_cvt_pk_bf16_f32 v15, v84, v85
	v_cvt_pk_bf16_f32 v16, v86, v87
	v_cvt_pk_bf16_f32 v17, v88, v89
	v_lshlrev_b32_e32 v22, 16, v14
	v_and_b32_e32 v23, 0xffff0000, v14
	v_sub_f32_e32 v82, v82, v22
	v_sub_f32_e32 v83, v83, v23
	v_cvt_pk_bf16_f32 v18, v82, v83
	v_lshlrev_b32_e32 v22, 16, v15
	v_and_b32_e32 v23, 0xffff0000, v15
	v_sub_f32_e32 v84, v84, v22
	v_sub_f32_e32 v85, v85, v23
	v_cvt_pk_bf16_f32 v19, v84, v85
	v_lshlrev_b32_e32 v22, 16, v16
	v_and_b32_e32 v23, 0xffff0000, v16
	v_sub_f32_e32 v86, v86, v22
	v_sub_f32_e32 v87, v87, v23
	v_cvt_pk_bf16_f32 v20, v86, v87
	v_lshlrev_b32_e32 v22, 16, v17
	v_and_b32_e32 v23, 0xffff0000, v17
	v_sub_f32_e32 v88, v88, v22
	v_sub_f32_e32 v89, v89, v23
	v_cvt_pk_bf16_f32 v21, v88, v89
	s_waitcnt lgkmcnt(0)
	v_mfma_f32_16x16x32_bf16 v[10:13], v[198:201], v[14:17], v[10:13]
	v_mfma_f32_16x16x32_bf16 v[6:9], v[206:209], v[14:17], v[6:9]
	v_mfma_f32_16x16x32_bf16 v[2:5], v[214:217], v[14:17], v[2:5]
	v_mfma_f32_16x16x32_bf16 v[10:13], v[198:201], v[18:21], v[10:13]
	ds_read_b128 v[198:201], v122 offset:1216
	v_mfma_f32_16x16x32_bf16 v[6:9], v[206:209], v[18:21], v[6:9]
	ds_read_b128 v[206:209], v122 offset:34240
	v_mfma_f32_16x16x32_bf16 v[2:5], v[214:217], v[18:21], v[2:5]
	ds_read_b128 v[214:217], v28 offset:1216
	v_mfma_f32_16x16x32_bf16 v[10:13], v[202:205], v[14:17], v[10:13]
	ds_read_b128 v[202:205], v123 offset:1216
	v_mfma_f32_16x16x32_bf16 v[6:9], v[210:213], v[14:17], v[6:9]
	ds_read_b128 v[210:213], v123 offset:34240
	v_mfma_f32_16x16x32_bf16 v[2:5], v[218:221], v[14:17], v[2:5]
	ds_read_b128 v[218:221], v29 offset:1216
	s_waitcnt vmcnt(48)
	v_cndmask_b32_e64 v24, v91, v90, vcc
	v_cndmask_b32_e64 v25, v93, v92, vcc
	v_cndmask_b32_e64 v26, v95, v94, vcc
	v_cndmask_b32_e64 v27, v97, v96, vcc
	v_mov_b32_dpp v222, v24 quad_perm:[1,0,3,2] row_mask:0xf bank_mask:0xf
	v_mov_b32_dpp v223, v25 quad_perm:[1,0,3,2] row_mask:0xf bank_mask:0xf
	v_mov_b32_dpp v224, v26 quad_perm:[1,0,3,2] row_mask:0xf bank_mask:0xf
	v_mov_b32_dpp v225, v27 quad_perm:[1,0,3,2] row_mask:0xf bank_mask:0xf
	v_cndmask_b32_e64 v90, v90, v222, vcc
	v_cndmask_b32_e64 v91, v222, v91, vcc
	v_cndmask_b32_e64 v92, v92, v223, vcc
	v_cndmask_b32_e64 v93, v223, v93, vcc
	v_cndmask_b32_e64 v94, v94, v224, vcc
	v_cndmask_b32_e64 v95, v224, v95, vcc
	v_cndmask_b32_e64 v96, v96, v225, vcc
	v_cndmask_b32_e64 v97, v225, v97, vcc
	v_cvt_pk_bf16_f32 v14, v90, v91
	v_cvt_pk_bf16_f32 v15, v92, v93
	v_cvt_pk_bf16_f32 v16, v94, v95
	v_cvt_pk_bf16_f32 v17, v96, v97
	v_lshlrev_b32_e32 v22, 16, v14
	v_and_b32_e32 v23, 0xffff0000, v14
	v_sub_f32_e32 v90, v90, v22
	v_sub_f32_e32 v91, v91, v23
	v_cvt_pk_bf16_f32 v18, v90, v91
	v_lshlrev_b32_e32 v22, 16, v15
	v_and_b32_e32 v23, 0xffff0000, v15
	v_sub_f32_e32 v92, v92, v22
	v_sub_f32_e32 v93, v93, v23
	v_cvt_pk_bf16_f32 v19, v92, v93
	v_lshlrev_b32_e32 v22, 16, v16
	v_and_b32_e32 v23, 0xffff0000, v16
	v_sub_f32_e32 v94, v94, v22
	v_sub_f32_e32 v95, v95, v23
	v_cvt_pk_bf16_f32 v20, v94, v95
	v_lshlrev_b32_e32 v22, 16, v17
	v_and_b32_e32 v23, 0xffff0000, v17
	v_sub_f32_e32 v96, v96, v22
	v_sub_f32_e32 v97, v97, v23
	v_cvt_pk_bf16_f32 v21, v96, v97
	s_waitcnt lgkmcnt(0)
	v_mfma_f32_16x16x32_bf16 v[10:13], v[198:201], v[14:17], v[10:13]
	v_mfma_f32_16x16x32_bf16 v[6:9], v[206:209], v[14:17], v[6:9]
	v_mfma_f32_16x16x32_bf16 v[2:5], v[214:217], v[14:17], v[2:5]
	v_mfma_f32_16x16x32_bf16 v[10:13], v[198:201], v[18:21], v[10:13]
	ds_read_b128 v[198:201], v122 offset:1280
	v_mfma_f32_16x16x32_bf16 v[6:9], v[206:209], v[18:21], v[6:9]
	ds_read_b128 v[206:209], v122 offset:34304
	v_mfma_f32_16x16x32_bf16 v[2:5], v[214:217], v[18:21], v[2:5]
	ds_read_b128 v[214:217], v28 offset:1280
	v_mfma_f32_16x16x32_bf16 v[10:13], v[202:205], v[14:17], v[10:13]
	ds_read_b128 v[202:205], v123 offset:1280
	v_mfma_f32_16x16x32_bf16 v[6:9], v[210:213], v[14:17], v[6:9]
	ds_read_b128 v[210:213], v123 offset:34304
	v_mfma_f32_16x16x32_bf16 v[2:5], v[218:221], v[14:17], v[2:5]
	ds_read_b128 v[218:221], v29 offset:1280
	s_waitcnt vmcnt(44)
	v_cndmask_b32_e64 v24, v99, v98, vcc
	v_cndmask_b32_e64 v25, v101, v100, vcc
	v_cndmask_b32_e64 v26, v103, v102, vcc
	v_cndmask_b32_e64 v27, v105, v104, vcc
	v_mov_b32_dpp v222, v24 quad_perm:[1,0,3,2] row_mask:0xf bank_mask:0xf
	v_mov_b32_dpp v223, v25 quad_perm:[1,0,3,2] row_mask:0xf bank_mask:0xf
	v_mov_b32_dpp v224, v26 quad_perm:[1,0,3,2] row_mask:0xf bank_mask:0xf
	v_mov_b32_dpp v225, v27 quad_perm:[1,0,3,2] row_mask:0xf bank_mask:0xf
	v_cndmask_b32_e64 v98, v98, v222, vcc
	v_cndmask_b32_e64 v99, v222, v99, vcc
	v_cndmask_b32_e64 v100, v100, v223, vcc
	v_cndmask_b32_e64 v101, v223, v101, vcc
	v_cndmask_b32_e64 v102, v102, v224, vcc
	v_cndmask_b32_e64 v103, v224, v103, vcc
	v_cndmask_b32_e64 v104, v104, v225, vcc
	v_cndmask_b32_e64 v105, v225, v105, vcc
	v_cvt_pk_bf16_f32 v14, v98, v99
	v_cvt_pk_bf16_f32 v15, v100, v101
	v_cvt_pk_bf16_f32 v16, v102, v103
	v_cvt_pk_bf16_f32 v17, v104, v105
	v_lshlrev_b32_e32 v22, 16, v14
	v_and_b32_e32 v23, 0xffff0000, v14
	v_sub_f32_e32 v98, v98, v22
	v_sub_f32_e32 v99, v99, v23
	v_cvt_pk_bf16_f32 v18, v98, v99
	v_lshlrev_b32_e32 v22, 16, v15
	v_and_b32_e32 v23, 0xffff0000, v15
	v_sub_f32_e32 v100, v100, v22
	v_sub_f32_e32 v101, v101, v23
	v_cvt_pk_bf16_f32 v19, v100, v101
	v_lshlrev_b32_e32 v22, 16, v16
	v_and_b32_e32 v23, 0xffff0000, v16
	v_sub_f32_e32 v102, v102, v22
	v_sub_f32_e32 v103, v103, v23
	v_cvt_pk_bf16_f32 v20, v102, v103
	v_lshlrev_b32_e32 v22, 16, v17
	v_and_b32_e32 v23, 0xffff0000, v17
	v_sub_f32_e32 v104, v104, v22
	v_sub_f32_e32 v105, v105, v23
	v_cvt_pk_bf16_f32 v21, v104, v105
	s_waitcnt lgkmcnt(0)
	v_mfma_f32_16x16x32_bf16 v[10:13], v[198:201], v[14:17], v[10:13]
	v_mfma_f32_16x16x32_bf16 v[6:9], v[206:209], v[14:17], v[6:9]
	v_mfma_f32_16x16x32_bf16 v[2:5], v[214:217], v[14:17], v[2:5]
	v_mfma_f32_16x16x32_bf16 v[10:13], v[198:201], v[18:21], v[10:13]
	ds_read_b128 v[198:201], v122 offset:1344
	v_mfma_f32_16x16x32_bf16 v[6:9], v[206:209], v[18:21], v[6:9]
	ds_read_b128 v[206:209], v122 offset:34368
	v_mfma_f32_16x16x32_bf16 v[2:5], v[214:217], v[18:21], v[2:5]
	ds_read_b128 v[214:217], v28 offset:1344
	v_mfma_f32_16x16x32_bf16 v[10:13], v[202:205], v[14:17], v[10:13]
	ds_read_b128 v[202:205], v123 offset:1344
	v_mfma_f32_16x16x32_bf16 v[6:9], v[210:213], v[14:17], v[6:9]
	ds_read_b128 v[210:213], v123 offset:34368
	v_mfma_f32_16x16x32_bf16 v[2:5], v[218:221], v[14:17], v[2:5]
	ds_read_b128 v[218:221], v29 offset:1344
	s_waitcnt vmcnt(40)
	v_cndmask_b32_e64 v24, v107, v106, vcc
	v_cndmask_b32_e64 v25, v109, v108, vcc
	v_cndmask_b32_e64 v26, v111, v110, vcc
	v_cndmask_b32_e64 v27, v113, v112, vcc
	v_mov_b32_dpp v222, v24 quad_perm:[1,0,3,2] row_mask:0xf bank_mask:0xf
	v_mov_b32_dpp v223, v25 quad_perm:[1,0,3,2] row_mask:0xf bank_mask:0xf
	v_mov_b32_dpp v224, v26 quad_perm:[1,0,3,2] row_mask:0xf bank_mask:0xf
	v_mov_b32_dpp v225, v27 quad_perm:[1,0,3,2] row_mask:0xf bank_mask:0xf
	v_cndmask_b32_e64 v106, v106, v222, vcc
	v_cndmask_b32_e64 v107, v222, v107, vcc
	v_cndmask_b32_e64 v108, v108, v223, vcc
	v_cndmask_b32_e64 v109, v223, v109, vcc
	v_cndmask_b32_e64 v110, v110, v224, vcc
	v_cndmask_b32_e64 v111, v224, v111, vcc
	v_cndmask_b32_e64 v112, v112, v225, vcc
	v_cndmask_b32_e64 v113, v225, v113, vcc
	v_cvt_pk_bf16_f32 v14, v106, v107
	v_cvt_pk_bf16_f32 v15, v108, v109
	v_cvt_pk_bf16_f32 v16, v110, v111
	v_cvt_pk_bf16_f32 v17, v112, v113
	v_lshlrev_b32_e32 v22, 16, v14
	v_and_b32_e32 v23, 0xffff0000, v14
	v_sub_f32_e32 v106, v106, v22
	v_sub_f32_e32 v107, v107, v23
	v_cvt_pk_bf16_f32 v18, v106, v107
	v_lshlrev_b32_e32 v22, 16, v15
	v_and_b32_e32 v23, 0xffff0000, v15
	v_sub_f32_e32 v108, v108, v22
	v_sub_f32_e32 v109, v109, v23
	v_cvt_pk_bf16_f32 v19, v108, v109
	v_lshlrev_b32_e32 v22, 16, v16
	v_and_b32_e32 v23, 0xffff0000, v16
	v_sub_f32_e32 v110, v110, v22
	v_sub_f32_e32 v111, v111, v23
	v_cvt_pk_bf16_f32 v20, v110, v111
	v_lshlrev_b32_e32 v22, 16, v17
	v_and_b32_e32 v23, 0xffff0000, v17
	v_sub_f32_e32 v112, v112, v22
	v_sub_f32_e32 v113, v113, v23
	v_cvt_pk_bf16_f32 v21, v112, v113
	s_waitcnt lgkmcnt(0)
	v_mfma_f32_16x16x32_bf16 v[10:13], v[198:201], v[14:17], v[10:13]
	v_mfma_f32_16x16x32_bf16 v[6:9], v[206:209], v[14:17], v[6:9]
	v_mfma_f32_16x16x32_bf16 v[2:5], v[214:217], v[14:17], v[2:5]
	v_mfma_f32_16x16x32_bf16 v[10:13], v[198:201], v[18:21], v[10:13]
	ds_read_b128 v[198:201], v122 offset:1408
	v_mfma_f32_16x16x32_bf16 v[6:9], v[206:209], v[18:21], v[6:9]
	ds_read_b128 v[206:209], v122 offset:34432
	v_mfma_f32_16x16x32_bf16 v[2:5], v[214:217], v[18:21], v[2:5]
	ds_read_b128 v[214:217], v28 offset:1408
	v_mfma_f32_16x16x32_bf16 v[10:13], v[202:205], v[14:17], v[10:13]
	ds_read_b128 v[202:205], v123 offset:1408
	v_mfma_f32_16x16x32_bf16 v[6:9], v[210:213], v[14:17], v[6:9]
	ds_read_b128 v[210:213], v123 offset:34432
	v_mfma_f32_16x16x32_bf16 v[2:5], v[218:221], v[14:17], v[2:5]
	ds_read_b128 v[218:221], v29 offset:1408
	s_waitcnt vmcnt(36)
	v_cndmask_b32_e64 v24, v115, v114, vcc
	v_cndmask_b32_e64 v25, v117, v116, vcc
	v_cndmask_b32_e64 v26, v119, v118, vcc
	v_cndmask_b32_e64 v27, v121, v120, vcc
	v_mov_b32_dpp v222, v24 quad_perm:[1,0,3,2] row_mask:0xf bank_mask:0xf
	v_mov_b32_dpp v223, v25 quad_perm:[1,0,3,2] row_mask:0xf bank_mask:0xf
	v_mov_b32_dpp v224, v26 quad_perm:[1,0,3,2] row_mask:0xf bank_mask:0xf
	v_mov_b32_dpp v225, v27 quad_perm:[1,0,3,2] row_mask:0xf bank_mask:0xf
	v_cndmask_b32_e64 v114, v114, v222, vcc
	v_cndmask_b32_e64 v115, v222, v115, vcc
	v_cndmask_b32_e64 v116, v116, v223, vcc
	v_cndmask_b32_e64 v117, v223, v117, vcc
	v_cndmask_b32_e64 v118, v118, v224, vcc
	v_cndmask_b32_e64 v119, v224, v119, vcc
	v_cndmask_b32_e64 v120, v120, v225, vcc
	v_cndmask_b32_e64 v121, v225, v121, vcc
	v_cvt_pk_bf16_f32 v14, v114, v115
	v_cvt_pk_bf16_f32 v15, v116, v117
	v_cvt_pk_bf16_f32 v16, v118, v119
	v_cvt_pk_bf16_f32 v17, v120, v121
	v_lshlrev_b32_e32 v22, 16, v14
	v_and_b32_e32 v23, 0xffff0000, v14
	v_sub_f32_e32 v114, v114, v22
	v_sub_f32_e32 v115, v115, v23
	v_cvt_pk_bf16_f32 v18, v114, v115
	v_lshlrev_b32_e32 v22, 16, v15
	v_and_b32_e32 v23, 0xffff0000, v15
	v_sub_f32_e32 v116, v116, v22
	v_sub_f32_e32 v117, v117, v23
	v_cvt_pk_bf16_f32 v19, v116, v117
	v_lshlrev_b32_e32 v22, 16, v16
	v_and_b32_e32 v23, 0xffff0000, v16
	v_sub_f32_e32 v118, v118, v22
	v_sub_f32_e32 v119, v119, v23
	v_cvt_pk_bf16_f32 v20, v118, v119
	v_lshlrev_b32_e32 v22, 16, v17
	v_and_b32_e32 v23, 0xffff0000, v17
	v_sub_f32_e32 v120, v120, v22
	v_sub_f32_e32 v121, v121, v23
	v_cvt_pk_bf16_f32 v21, v120, v121
	s_waitcnt lgkmcnt(0)
	v_mfma_f32_16x16x32_bf16 v[10:13], v[198:201], v[14:17], v[10:13]
	v_mfma_f32_16x16x32_bf16 v[6:9], v[206:209], v[14:17], v[6:9]
	v_mfma_f32_16x16x32_bf16 v[2:5], v[214:217], v[14:17], v[2:5]
	v_mfma_f32_16x16x32_bf16 v[10:13], v[198:201], v[18:21], v[10:13]
	ds_read_b128 v[198:201], v122 offset:1472
	v_mfma_f32_16x16x32_bf16 v[6:9], v[206:209], v[18:21], v[6:9]
	ds_read_b128 v[206:209], v122 offset:34496
	v_mfma_f32_16x16x32_bf16 v[2:5], v[214:217], v[18:21], v[2:5]
	ds_read_b128 v[214:217], v28 offset:1472
	v_mfma_f32_16x16x32_bf16 v[10:13], v[202:205], v[14:17], v[10:13]
	ds_read_b128 v[202:205], v123 offset:1472
	v_mfma_f32_16x16x32_bf16 v[6:9], v[210:213], v[14:17], v[6:9]
	ds_read_b128 v[210:213], v123 offset:34496
	v_mfma_f32_16x16x32_bf16 v[2:5], v[218:221], v[14:17], v[2:5]
	ds_read_b128 v[218:221], v29 offset:1472
	s_waitcnt vmcnt(32)
	v_cndmask_b32_e64 v24, v127, v126, vcc
	v_cndmask_b32_e64 v25, v129, v128, vcc
	v_cndmask_b32_e64 v26, v131, v130, vcc
	v_cndmask_b32_e64 v27, v133, v132, vcc
	v_mov_b32_dpp v222, v24 quad_perm:[1,0,3,2] row_mask:0xf bank_mask:0xf
	v_mov_b32_dpp v223, v25 quad_perm:[1,0,3,2] row_mask:0xf bank_mask:0xf
	v_mov_b32_dpp v224, v26 quad_perm:[1,0,3,2] row_mask:0xf bank_mask:0xf
	v_mov_b32_dpp v225, v27 quad_perm:[1,0,3,2] row_mask:0xf bank_mask:0xf
	v_cndmask_b32_e64 v126, v126, v222, vcc
	v_cndmask_b32_e64 v127, v222, v127, vcc
	v_cndmask_b32_e64 v128, v128, v223, vcc
	v_cndmask_b32_e64 v129, v223, v129, vcc
	v_cndmask_b32_e64 v130, v130, v224, vcc
	v_cndmask_b32_e64 v131, v224, v131, vcc
	v_cndmask_b32_e64 v132, v132, v225, vcc
	v_cndmask_b32_e64 v133, v225, v133, vcc
	v_cvt_pk_bf16_f32 v14, v126, v127
	v_cvt_pk_bf16_f32 v15, v128, v129
	v_cvt_pk_bf16_f32 v16, v130, v131
	v_cvt_pk_bf16_f32 v17, v132, v133
	v_lshlrev_b32_e32 v22, 16, v14
	v_and_b32_e32 v23, 0xffff0000, v14
	v_sub_f32_e32 v126, v126, v22
	v_sub_f32_e32 v127, v127, v23
	v_cvt_pk_bf16_f32 v18, v126, v127
	v_lshlrev_b32_e32 v22, 16, v15
	v_and_b32_e32 v23, 0xffff0000, v15
	v_sub_f32_e32 v128, v128, v22
	v_sub_f32_e32 v129, v129, v23
	v_cvt_pk_bf16_f32 v19, v128, v129
	v_lshlrev_b32_e32 v22, 16, v16
	v_and_b32_e32 v23, 0xffff0000, v16
	v_sub_f32_e32 v130, v130, v22
	v_sub_f32_e32 v131, v131, v23
	v_cvt_pk_bf16_f32 v20, v130, v131
	v_lshlrev_b32_e32 v22, 16, v17
	v_and_b32_e32 v23, 0xffff0000, v17
	v_sub_f32_e32 v132, v132, v22
	v_sub_f32_e32 v133, v133, v23
	v_cvt_pk_bf16_f32 v21, v132, v133
	s_waitcnt lgkmcnt(0)
	v_mfma_f32_16x16x32_bf16 v[10:13], v[198:201], v[14:17], v[10:13]
	v_mfma_f32_16x16x32_bf16 v[6:9], v[206:209], v[14:17], v[6:9]
	v_mfma_f32_16x16x32_bf16 v[2:5], v[214:217], v[14:17], v[2:5]
	v_mfma_f32_16x16x32_bf16 v[10:13], v[198:201], v[18:21], v[10:13]
	ds_read_b128 v[198:201], v122 offset:1536
	v_mfma_f32_16x16x32_bf16 v[6:9], v[206:209], v[18:21], v[6:9]
	ds_read_b128 v[206:209], v122 offset:34560
	v_mfma_f32_16x16x32_bf16 v[2:5], v[214:217], v[18:21], v[2:5]
	ds_read_b128 v[214:217], v28 offset:1536
	v_mfma_f32_16x16x32_bf16 v[10:13], v[202:205], v[14:17], v[10:13]
	ds_read_b128 v[202:205], v123 offset:1536
	v_mfma_f32_16x16x32_bf16 v[6:9], v[210:213], v[14:17], v[6:9]
	ds_read_b128 v[210:213], v123 offset:34560
	v_mfma_f32_16x16x32_bf16 v[2:5], v[218:221], v[14:17], v[2:5]
	ds_read_b128 v[218:221], v29 offset:1536
	s_waitcnt vmcnt(28)
	v_cndmask_b32_e64 v24, v135, v134, vcc
	v_cndmask_b32_e64 v25, v137, v136, vcc
	v_cndmask_b32_e64 v26, v139, v138, vcc
	v_cndmask_b32_e64 v27, v141, v140, vcc
	v_mov_b32_dpp v222, v24 quad_perm:[1,0,3,2] row_mask:0xf bank_mask:0xf
	v_mov_b32_dpp v223, v25 quad_perm:[1,0,3,2] row_mask:0xf bank_mask:0xf
	v_mov_b32_dpp v224, v26 quad_perm:[1,0,3,2] row_mask:0xf bank_mask:0xf
	v_mov_b32_dpp v225, v27 quad_perm:[1,0,3,2] row_mask:0xf bank_mask:0xf
	v_cndmask_b32_e64 v134, v134, v222, vcc
	v_cndmask_b32_e64 v135, v222, v135, vcc
	v_cndmask_b32_e64 v136, v136, v223, vcc
	v_cndmask_b32_e64 v137, v223, v137, vcc
	v_cndmask_b32_e64 v138, v138, v224, vcc
	v_cndmask_b32_e64 v139, v224, v139, vcc
	v_cndmask_b32_e64 v140, v140, v225, vcc
	v_cndmask_b32_e64 v141, v225, v141, vcc
	v_cvt_pk_bf16_f32 v14, v134, v135
	v_cvt_pk_bf16_f32 v15, v136, v137
	v_cvt_pk_bf16_f32 v16, v138, v139
	v_cvt_pk_bf16_f32 v17, v140, v141
	v_lshlrev_b32_e32 v22, 16, v14
	v_and_b32_e32 v23, 0xffff0000, v14
	v_sub_f32_e32 v134, v134, v22
	v_sub_f32_e32 v135, v135, v23
	v_cvt_pk_bf16_f32 v18, v134, v135
	v_lshlrev_b32_e32 v22, 16, v15
	v_and_b32_e32 v23, 0xffff0000, v15
	v_sub_f32_e32 v136, v136, v22
	v_sub_f32_e32 v137, v137, v23
	v_cvt_pk_bf16_f32 v19, v136, v137
	v_lshlrev_b32_e32 v22, 16, v16
	v_and_b32_e32 v23, 0xffff0000, v16
	v_sub_f32_e32 v138, v138, v22
	v_sub_f32_e32 v139, v139, v23
	v_cvt_pk_bf16_f32 v20, v138, v139
	v_lshlrev_b32_e32 v22, 16, v17
	v_and_b32_e32 v23, 0xffff0000, v17
	v_sub_f32_e32 v140, v140, v22
	v_sub_f32_e32 v141, v141, v23
	v_cvt_pk_bf16_f32 v21, v140, v141
	s_waitcnt lgkmcnt(0)
	v_mfma_f32_16x16x32_bf16 v[10:13], v[198:201], v[14:17], v[10:13]
	v_mfma_f32_16x16x32_bf16 v[6:9], v[206:209], v[14:17], v[6:9]
	v_mfma_f32_16x16x32_bf16 v[2:5], v[214:217], v[14:17], v[2:5]
	v_mfma_f32_16x16x32_bf16 v[10:13], v[198:201], v[18:21], v[10:13]
	ds_read_b128 v[198:201], v122 offset:1600
	v_mfma_f32_16x16x32_bf16 v[6:9], v[206:209], v[18:21], v[6:9]
	ds_read_b128 v[206:209], v122 offset:34624
	v_mfma_f32_16x16x32_bf16 v[2:5], v[214:217], v[18:21], v[2:5]
	ds_read_b128 v[214:217], v28 offset:1600
	v_mfma_f32_16x16x32_bf16 v[10:13], v[202:205], v[14:17], v[10:13]
	ds_read_b128 v[202:205], v123 offset:1600
	v_mfma_f32_16x16x32_bf16 v[6:9], v[210:213], v[14:17], v[6:9]
	ds_read_b128 v[210:213], v123 offset:34624
	v_mfma_f32_16x16x32_bf16 v[2:5], v[218:221], v[14:17], v[2:5]
	ds_read_b128 v[218:221], v29 offset:1600
	s_waitcnt vmcnt(24)
	v_cndmask_b32_e64 v24, v143, v142, vcc
	v_cndmask_b32_e64 v25, v145, v144, vcc
	v_cndmask_b32_e64 v26, v147, v146, vcc
	v_cndmask_b32_e64 v27, v149, v148, vcc
	v_mov_b32_dpp v222, v24 quad_perm:[1,0,3,2] row_mask:0xf bank_mask:0xf
	v_mov_b32_dpp v223, v25 quad_perm:[1,0,3,2] row_mask:0xf bank_mask:0xf
	v_mov_b32_dpp v224, v26 quad_perm:[1,0,3,2] row_mask:0xf bank_mask:0xf
	v_mov_b32_dpp v225, v27 quad_perm:[1,0,3,2] row_mask:0xf bank_mask:0xf
	v_cndmask_b32_e64 v142, v142, v222, vcc
	v_cndmask_b32_e64 v143, v222, v143, vcc
	v_cndmask_b32_e64 v144, v144, v223, vcc
	v_cndmask_b32_e64 v145, v223, v145, vcc
	v_cndmask_b32_e64 v146, v146, v224, vcc
	v_cndmask_b32_e64 v147, v224, v147, vcc
	v_cndmask_b32_e64 v148, v148, v225, vcc
	v_cndmask_b32_e64 v149, v225, v149, vcc
	v_cvt_pk_bf16_f32 v14, v142, v143
	v_cvt_pk_bf16_f32 v15, v144, v145
	v_cvt_pk_bf16_f32 v16, v146, v147
	v_cvt_pk_bf16_f32 v17, v148, v149
	v_lshlrev_b32_e32 v22, 16, v14
	v_and_b32_e32 v23, 0xffff0000, v14
	v_sub_f32_e32 v142, v142, v22
	v_sub_f32_e32 v143, v143, v23
	v_cvt_pk_bf16_f32 v18, v142, v143
	v_lshlrev_b32_e32 v22, 16, v15
	v_and_b32_e32 v23, 0xffff0000, v15
	v_sub_f32_e32 v144, v144, v22
	v_sub_f32_e32 v145, v145, v23
	v_cvt_pk_bf16_f32 v19, v144, v145
	v_lshlrev_b32_e32 v22, 16, v16
	v_and_b32_e32 v23, 0xffff0000, v16
	v_sub_f32_e32 v146, v146, v22
	v_sub_f32_e32 v147, v147, v23
	v_cvt_pk_bf16_f32 v20, v146, v147
	v_lshlrev_b32_e32 v22, 16, v17
	v_and_b32_e32 v23, 0xffff0000, v17
	v_sub_f32_e32 v148, v148, v22
	v_sub_f32_e32 v149, v149, v23
	v_cvt_pk_bf16_f32 v21, v148, v149
	s_waitcnt lgkmcnt(0)
	v_mfma_f32_16x16x32_bf16 v[10:13], v[198:201], v[14:17], v[10:13]
	v_mfma_f32_16x16x32_bf16 v[6:9], v[206:209], v[14:17], v[6:9]
	v_mfma_f32_16x16x32_bf16 v[2:5], v[214:217], v[14:17], v[2:5]
	v_mfma_f32_16x16x32_bf16 v[10:13], v[198:201], v[18:21], v[10:13]
	ds_read_b128 v[198:201], v122 offset:1664
	v_mfma_f32_16x16x32_bf16 v[6:9], v[206:209], v[18:21], v[6:9]
	ds_read_b128 v[206:209], v122 offset:34688
	v_mfma_f32_16x16x32_bf16 v[2:5], v[214:217], v[18:21], v[2:5]
	ds_read_b128 v[214:217], v28 offset:1664
	v_mfma_f32_16x16x32_bf16 v[10:13], v[202:205], v[14:17], v[10:13]
	ds_read_b128 v[202:205], v123 offset:1664
	v_mfma_f32_16x16x32_bf16 v[6:9], v[210:213], v[14:17], v[6:9]
	ds_read_b128 v[210:213], v123 offset:34688
	v_mfma_f32_16x16x32_bf16 v[2:5], v[218:221], v[14:17], v[2:5]
	ds_read_b128 v[218:221], v29 offset:1664
	s_waitcnt vmcnt(20)
	v_cndmask_b32_e64 v24, v151, v150, vcc
	v_cndmask_b32_e64 v25, v153, v152, vcc
	v_cndmask_b32_e64 v26, v155, v154, vcc
	v_cndmask_b32_e64 v27, v157, v156, vcc
	v_mov_b32_dpp v222, v24 quad_perm:[1,0,3,2] row_mask:0xf bank_mask:0xf
	v_mov_b32_dpp v223, v25 quad_perm:[1,0,3,2] row_mask:0xf bank_mask:0xf
	v_mov_b32_dpp v224, v26 quad_perm:[1,0,3,2] row_mask:0xf bank_mask:0xf
	v_mov_b32_dpp v225, v27 quad_perm:[1,0,3,2] row_mask:0xf bank_mask:0xf
	v_cndmask_b32_e64 v150, v150, v222, vcc
	v_cndmask_b32_e64 v151, v222, v151, vcc
	v_cndmask_b32_e64 v152, v152, v223, vcc
	v_cndmask_b32_e64 v153, v223, v153, vcc
	v_cndmask_b32_e64 v154, v154, v224, vcc
	v_cndmask_b32_e64 v155, v224, v155, vcc
	v_cndmask_b32_e64 v156, v156, v225, vcc
	v_cndmask_b32_e64 v157, v225, v157, vcc
	v_cvt_pk_bf16_f32 v14, v150, v151
	v_cvt_pk_bf16_f32 v15, v152, v153
	v_cvt_pk_bf16_f32 v16, v154, v155
	v_cvt_pk_bf16_f32 v17, v156, v157
	v_lshlrev_b32_e32 v22, 16, v14
	v_and_b32_e32 v23, 0xffff0000, v14
	v_sub_f32_e32 v150, v150, v22
	v_sub_f32_e32 v151, v151, v23
	v_cvt_pk_bf16_f32 v18, v150, v151
	v_lshlrev_b32_e32 v22, 16, v15
	v_and_b32_e32 v23, 0xffff0000, v15
	v_sub_f32_e32 v152, v152, v22
	v_sub_f32_e32 v153, v153, v23
	v_cvt_pk_bf16_f32 v19, v152, v153
	v_lshlrev_b32_e32 v22, 16, v16
	v_and_b32_e32 v23, 0xffff0000, v16
	v_sub_f32_e32 v154, v154, v22
	v_sub_f32_e32 v155, v155, v23
	v_cvt_pk_bf16_f32 v20, v154, v155
	v_lshlrev_b32_e32 v22, 16, v17
	v_and_b32_e32 v23, 0xffff0000, v17
	v_sub_f32_e32 v156, v156, v22
	v_sub_f32_e32 v157, v157, v23
	v_cvt_pk_bf16_f32 v21, v156, v157
	s_waitcnt lgkmcnt(0)
	v_mfma_f32_16x16x32_bf16 v[10:13], v[198:201], v[14:17], v[10:13]
	v_mfma_f32_16x16x32_bf16 v[6:9], v[206:209], v[14:17], v[6:9]
	v_mfma_f32_16x16x32_bf16 v[2:5], v[214:217], v[14:17], v[2:5]
	v_mfma_f32_16x16x32_bf16 v[10:13], v[198:201], v[18:21], v[10:13]
	ds_read_b128 v[198:201], v122 offset:1728
	v_mfma_f32_16x16x32_bf16 v[6:9], v[206:209], v[18:21], v[6:9]
	ds_read_b128 v[206:209], v122 offset:34752
	v_mfma_f32_16x16x32_bf16 v[2:5], v[214:217], v[18:21], v[2:5]
	ds_read_b128 v[214:217], v28 offset:1728
	v_mfma_f32_16x16x32_bf16 v[10:13], v[202:205], v[14:17], v[10:13]
	ds_read_b128 v[202:205], v123 offset:1728
	v_mfma_f32_16x16x32_bf16 v[6:9], v[210:213], v[14:17], v[6:9]
	ds_read_b128 v[210:213], v123 offset:34752
	v_mfma_f32_16x16x32_bf16 v[2:5], v[218:221], v[14:17], v[2:5]
	ds_read_b128 v[218:221], v29 offset:1728
	s_waitcnt vmcnt(16)
	v_cndmask_b32_e64 v24, v159, v158, vcc
	v_cndmask_b32_e64 v25, v161, v160, vcc
	v_cndmask_b32_e64 v26, v163, v162, vcc
	v_cndmask_b32_e64 v27, v165, v164, vcc
	v_mov_b32_dpp v222, v24 quad_perm:[1,0,3,2] row_mask:0xf bank_mask:0xf
	v_mov_b32_dpp v223, v25 quad_perm:[1,0,3,2] row_mask:0xf bank_mask:0xf
	v_mov_b32_dpp v224, v26 quad_perm:[1,0,3,2] row_mask:0xf bank_mask:0xf
	v_mov_b32_dpp v225, v27 quad_perm:[1,0,3,2] row_mask:0xf bank_mask:0xf
	v_cndmask_b32_e64 v158, v158, v222, vcc
	v_cndmask_b32_e64 v159, v222, v159, vcc
	v_cndmask_b32_e64 v160, v160, v223, vcc
	v_cndmask_b32_e64 v161, v223, v161, vcc
	v_cndmask_b32_e64 v162, v162, v224, vcc
	v_cndmask_b32_e64 v163, v224, v163, vcc
	v_cndmask_b32_e64 v164, v164, v225, vcc
	v_cndmask_b32_e64 v165, v225, v165, vcc
	v_cvt_pk_bf16_f32 v14, v158, v159
	v_cvt_pk_bf16_f32 v15, v160, v161
	v_cvt_pk_bf16_f32 v16, v162, v163
	v_cvt_pk_bf16_f32 v17, v164, v165
	v_lshlrev_b32_e32 v22, 16, v14
	v_and_b32_e32 v23, 0xffff0000, v14
	v_sub_f32_e32 v158, v158, v22
	v_sub_f32_e32 v159, v159, v23
	v_cvt_pk_bf16_f32 v18, v158, v159
	v_lshlrev_b32_e32 v22, 16, v15
	v_and_b32_e32 v23, 0xffff0000, v15
	v_sub_f32_e32 v160, v160, v22
	v_sub_f32_e32 v161, v161, v23
	v_cvt_pk_bf16_f32 v19, v160, v161
	v_lshlrev_b32_e32 v22, 16, v16
	v_and_b32_e32 v23, 0xffff0000, v16
	v_sub_f32_e32 v162, v162, v22
	v_sub_f32_e32 v163, v163, v23
	v_cvt_pk_bf16_f32 v20, v162, v163
	v_lshlrev_b32_e32 v22, 16, v17
	v_and_b32_e32 v23, 0xffff0000, v17
	v_sub_f32_e32 v164, v164, v22
	v_sub_f32_e32 v165, v165, v23
	v_cvt_pk_bf16_f32 v21, v164, v165
	s_waitcnt lgkmcnt(0)
	v_mfma_f32_16x16x32_bf16 v[10:13], v[198:201], v[14:17], v[10:13]
	v_mfma_f32_16x16x32_bf16 v[6:9], v[206:209], v[14:17], v[6:9]
	v_mfma_f32_16x16x32_bf16 v[2:5], v[214:217], v[14:17], v[2:5]
	v_mfma_f32_16x16x32_bf16 v[10:13], v[198:201], v[18:21], v[10:13]
	ds_read_b128 v[198:201], v122 offset:1792
	v_mfma_f32_16x16x32_bf16 v[6:9], v[206:209], v[18:21], v[6:9]
	ds_read_b128 v[206:209], v122 offset:34816
	v_mfma_f32_16x16x32_bf16 v[2:5], v[214:217], v[18:21], v[2:5]
	ds_read_b128 v[214:217], v28 offset:1792
	v_mfma_f32_16x16x32_bf16 v[10:13], v[202:205], v[14:17], v[10:13]
	ds_read_b128 v[202:205], v123 offset:1792
	v_mfma_f32_16x16x32_bf16 v[6:9], v[210:213], v[14:17], v[6:9]
	ds_read_b128 v[210:213], v123 offset:34816
	v_mfma_f32_16x16x32_bf16 v[2:5], v[218:221], v[14:17], v[2:5]
	ds_read_b128 v[218:221], v29 offset:1792
	s_waitcnt vmcnt(12)
	v_cndmask_b32_e64 v24, v167, v166, vcc
	v_cndmask_b32_e64 v25, v169, v168, vcc
	v_cndmask_b32_e64 v26, v171, v170, vcc
	v_cndmask_b32_e64 v27, v173, v172, vcc
	v_mov_b32_dpp v222, v24 quad_perm:[1,0,3,2] row_mask:0xf bank_mask:0xf
	v_mov_b32_dpp v223, v25 quad_perm:[1,0,3,2] row_mask:0xf bank_mask:0xf
	v_mov_b32_dpp v224, v26 quad_perm:[1,0,3,2] row_mask:0xf bank_mask:0xf
	v_mov_b32_dpp v225, v27 quad_perm:[1,0,3,2] row_mask:0xf bank_mask:0xf
	v_cndmask_b32_e64 v166, v166, v222, vcc
	v_cndmask_b32_e64 v167, v222, v167, vcc
	v_cndmask_b32_e64 v168, v168, v223, vcc
	v_cndmask_b32_e64 v169, v223, v169, vcc
	v_cndmask_b32_e64 v170, v170, v224, vcc
	v_cndmask_b32_e64 v171, v224, v171, vcc
	v_cndmask_b32_e64 v172, v172, v225, vcc
	v_cndmask_b32_e64 v173, v225, v173, vcc
	v_cvt_pk_bf16_f32 v14, v166, v167
	v_cvt_pk_bf16_f32 v15, v168, v169
	v_cvt_pk_bf16_f32 v16, v170, v171
	v_cvt_pk_bf16_f32 v17, v172, v173
	v_lshlrev_b32_e32 v22, 16, v14
	v_and_b32_e32 v23, 0xffff0000, v14
	v_sub_f32_e32 v166, v166, v22
	v_sub_f32_e32 v167, v167, v23
	v_cvt_pk_bf16_f32 v18, v166, v167
	v_lshlrev_b32_e32 v22, 16, v15
	v_and_b32_e32 v23, 0xffff0000, v15
	v_sub_f32_e32 v168, v168, v22
	v_sub_f32_e32 v169, v169, v23
	v_cvt_pk_bf16_f32 v19, v168, v169
	v_lshlrev_b32_e32 v22, 16, v16
	v_and_b32_e32 v23, 0xffff0000, v16
	v_sub_f32_e32 v170, v170, v22
	v_sub_f32_e32 v171, v171, v23
	v_cvt_pk_bf16_f32 v20, v170, v171
	v_lshlrev_b32_e32 v22, 16, v17
	v_and_b32_e32 v23, 0xffff0000, v17
	v_sub_f32_e32 v172, v172, v22
	v_sub_f32_e32 v173, v173, v23
	v_cvt_pk_bf16_f32 v21, v172, v173
	s_waitcnt lgkmcnt(0)
	v_mfma_f32_16x16x32_bf16 v[10:13], v[198:201], v[14:17], v[10:13]
	v_mfma_f32_16x16x32_bf16 v[6:9], v[206:209], v[14:17], v[6:9]
	v_mfma_f32_16x16x32_bf16 v[2:5], v[214:217], v[14:17], v[2:5]
	v_mfma_f32_16x16x32_bf16 v[10:13], v[198:201], v[18:21], v[10:13]
	ds_read_b128 v[198:201], v122 offset:1856
	v_mfma_f32_16x16x32_bf16 v[6:9], v[206:209], v[18:21], v[6:9]
	ds_read_b128 v[206:209], v122 offset:34880
	v_mfma_f32_16x16x32_bf16 v[2:5], v[214:217], v[18:21], v[2:5]
	ds_read_b128 v[214:217], v28 offset:1856
	v_mfma_f32_16x16x32_bf16 v[10:13], v[202:205], v[14:17], v[10:13]
	ds_read_b128 v[202:205], v123 offset:1856
	v_mfma_f32_16x16x32_bf16 v[6:9], v[210:213], v[14:17], v[6:9]
	ds_read_b128 v[210:213], v123 offset:34880
	v_mfma_f32_16x16x32_bf16 v[2:5], v[218:221], v[14:17], v[2:5]
	ds_read_b128 v[218:221], v29 offset:1856
	s_waitcnt vmcnt(8)
	v_cndmask_b32_e64 v24, v175, v174, vcc
	v_cndmask_b32_e64 v25, v177, v176, vcc
	v_cndmask_b32_e64 v26, v179, v178, vcc
	v_cndmask_b32_e64 v27, v181, v180, vcc
	v_mov_b32_dpp v222, v24 quad_perm:[1,0,3,2] row_mask:0xf bank_mask:0xf
	v_mov_b32_dpp v223, v25 quad_perm:[1,0,3,2] row_mask:0xf bank_mask:0xf
	v_mov_b32_dpp v224, v26 quad_perm:[1,0,3,2] row_mask:0xf bank_mask:0xf
	v_mov_b32_dpp v225, v27 quad_perm:[1,0,3,2] row_mask:0xf bank_mask:0xf
	v_cndmask_b32_e64 v174, v174, v222, vcc
	v_cndmask_b32_e64 v175, v222, v175, vcc
	v_cndmask_b32_e64 v176, v176, v223, vcc
	v_cndmask_b32_e64 v177, v223, v177, vcc
	v_cndmask_b32_e64 v178, v178, v224, vcc
	v_cndmask_b32_e64 v179, v224, v179, vcc
	v_cndmask_b32_e64 v180, v180, v225, vcc
	v_cndmask_b32_e64 v181, v225, v181, vcc
	v_cvt_pk_bf16_f32 v14, v174, v175
	v_cvt_pk_bf16_f32 v15, v176, v177
	v_cvt_pk_bf16_f32 v16, v178, v179
	v_cvt_pk_bf16_f32 v17, v180, v181
	v_lshlrev_b32_e32 v22, 16, v14
	v_and_b32_e32 v23, 0xffff0000, v14
	v_sub_f32_e32 v174, v174, v22
	v_sub_f32_e32 v175, v175, v23
	v_cvt_pk_bf16_f32 v18, v174, v175
	v_lshlrev_b32_e32 v22, 16, v15
	v_and_b32_e32 v23, 0xffff0000, v15
	v_sub_f32_e32 v176, v176, v22
	v_sub_f32_e32 v177, v177, v23
	v_cvt_pk_bf16_f32 v19, v176, v177
	v_lshlrev_b32_e32 v22, 16, v16
	v_and_b32_e32 v23, 0xffff0000, v16
	v_sub_f32_e32 v178, v178, v22
	v_sub_f32_e32 v179, v179, v23
	v_cvt_pk_bf16_f32 v20, v178, v179
	v_lshlrev_b32_e32 v22, 16, v17
	v_and_b32_e32 v23, 0xffff0000, v17
	v_sub_f32_e32 v180, v180, v22
	v_sub_f32_e32 v181, v181, v23
	v_cvt_pk_bf16_f32 v21, v180, v181
	s_waitcnt lgkmcnt(0)
	v_mfma_f32_16x16x32_bf16 v[10:13], v[198:201], v[14:17], v[10:13]
	v_mfma_f32_16x16x32_bf16 v[6:9], v[206:209], v[14:17], v[6:9]
	v_mfma_f32_16x16x32_bf16 v[2:5], v[214:217], v[14:17], v[2:5]
	v_mfma_f32_16x16x32_bf16 v[10:13], v[198:201], v[18:21], v[10:13]
	ds_read_b128 v[198:201], v122 offset:1920
	v_mfma_f32_16x16x32_bf16 v[6:9], v[206:209], v[18:21], v[6:9]
	ds_read_b128 v[206:209], v122 offset:34944
	v_mfma_f32_16x16x32_bf16 v[2:5], v[214:217], v[18:21], v[2:5]
	ds_read_b128 v[214:217], v28 offset:1920
	v_mfma_f32_16x16x32_bf16 v[10:13], v[202:205], v[14:17], v[10:13]
	ds_read_b128 v[202:205], v123 offset:1920
	v_mfma_f32_16x16x32_bf16 v[6:9], v[210:213], v[14:17], v[6:9]
	ds_read_b128 v[210:213], v123 offset:34944
	v_mfma_f32_16x16x32_bf16 v[2:5], v[218:221], v[14:17], v[2:5]
	ds_read_b128 v[218:221], v29 offset:1920
	s_waitcnt vmcnt(4)
	v_cndmask_b32_e64 v24, v183, v182, vcc
	v_cndmask_b32_e64 v25, v185, v184, vcc
	v_cndmask_b32_e64 v26, v187, v186, vcc
	v_cndmask_b32_e64 v27, v189, v188, vcc
	v_mov_b32_dpp v222, v24 quad_perm:[1,0,3,2] row_mask:0xf bank_mask:0xf
	v_mov_b32_dpp v223, v25 quad_perm:[1,0,3,2] row_mask:0xf bank_mask:0xf
	v_mov_b32_dpp v224, v26 quad_perm:[1,0,3,2] row_mask:0xf bank_mask:0xf
	v_mov_b32_dpp v225, v27 quad_perm:[1,0,3,2] row_mask:0xf bank_mask:0xf
	v_cndmask_b32_e64 v182, v182, v222, vcc
	v_cndmask_b32_e64 v183, v222, v183, vcc
	v_cndmask_b32_e64 v184, v184, v223, vcc
	v_cndmask_b32_e64 v185, v223, v185, vcc
	v_cndmask_b32_e64 v186, v186, v224, vcc
	v_cndmask_b32_e64 v187, v224, v187, vcc
	v_cndmask_b32_e64 v188, v188, v225, vcc
	v_cndmask_b32_e64 v189, v225, v189, vcc
	v_cvt_pk_bf16_f32 v14, v182, v183
	v_cvt_pk_bf16_f32 v15, v184, v185
	v_cvt_pk_bf16_f32 v16, v186, v187
	v_cvt_pk_bf16_f32 v17, v188, v189
	v_lshlrev_b32_e32 v22, 16, v14
	v_and_b32_e32 v23, 0xffff0000, v14
	v_sub_f32_e32 v182, v182, v22
	v_sub_f32_e32 v183, v183, v23
	v_cvt_pk_bf16_f32 v18, v182, v183
	v_lshlrev_b32_e32 v22, 16, v15
	v_and_b32_e32 v23, 0xffff0000, v15
	v_sub_f32_e32 v184, v184, v22
	v_sub_f32_e32 v185, v185, v23
	v_cvt_pk_bf16_f32 v19, v184, v185
	v_lshlrev_b32_e32 v22, 16, v16
	v_and_b32_e32 v23, 0xffff0000, v16
	v_sub_f32_e32 v186, v186, v22
	v_sub_f32_e32 v187, v187, v23
	v_cvt_pk_bf16_f32 v20, v186, v187
	v_lshlrev_b32_e32 v22, 16, v17
	v_and_b32_e32 v23, 0xffff0000, v17
	v_sub_f32_e32 v188, v188, v22
	v_sub_f32_e32 v189, v189, v23
	v_cvt_pk_bf16_f32 v21, v188, v189
	s_waitcnt lgkmcnt(0)
	v_mfma_f32_16x16x32_bf16 v[10:13], v[198:201], v[14:17], v[10:13]
	v_mfma_f32_16x16x32_bf16 v[6:9], v[206:209], v[14:17], v[6:9]
	v_mfma_f32_16x16x32_bf16 v[2:5], v[214:217], v[14:17], v[2:5]
	v_mfma_f32_16x16x32_bf16 v[10:13], v[198:201], v[18:21], v[10:13]
	ds_read_b128 v[198:201], v122 offset:1984
	v_mfma_f32_16x16x32_bf16 v[6:9], v[206:209], v[18:21], v[6:9]
	ds_read_b128 v[206:209], v122 offset:35008
	v_mfma_f32_16x16x32_bf16 v[2:5], v[214:217], v[18:21], v[2:5]
	ds_read_b128 v[214:217], v28 offset:1984
	v_mfma_f32_16x16x32_bf16 v[10:13], v[202:205], v[14:17], v[10:13]
	ds_read_b128 v[202:205], v123 offset:1984
	v_mfma_f32_16x16x32_bf16 v[6:9], v[210:213], v[14:17], v[6:9]
	ds_read_b128 v[210:213], v123 offset:35008
	v_mfma_f32_16x16x32_bf16 v[2:5], v[218:221], v[14:17], v[2:5]
	ds_read_b128 v[218:221], v29 offset:1984
	s_waitcnt vmcnt(0)
	v_cndmask_b32_e64 v24, v191, v190, vcc
	v_cndmask_b32_e64 v25, v193, v192, vcc
	v_cndmask_b32_e64 v26, v195, v194, vcc
	v_cndmask_b32_e64 v27, v197, v196, vcc
	v_mov_b32_dpp v222, v24 quad_perm:[1,0,3,2] row_mask:0xf bank_mask:0xf
	v_mov_b32_dpp v223, v25 quad_perm:[1,0,3,2] row_mask:0xf bank_mask:0xf
	v_mov_b32_dpp v224, v26 quad_perm:[1,0,3,2] row_mask:0xf bank_mask:0xf
	v_mov_b32_dpp v225, v27 quad_perm:[1,0,3,2] row_mask:0xf bank_mask:0xf
	v_cndmask_b32_e64 v190, v190, v222, vcc
	v_cndmask_b32_e64 v191, v222, v191, vcc
	v_cndmask_b32_e64 v192, v192, v223, vcc
	v_cndmask_b32_e64 v193, v223, v193, vcc
	v_cndmask_b32_e64 v194, v194, v224, vcc
	v_cndmask_b32_e64 v195, v224, v195, vcc
	v_cndmask_b32_e64 v196, v196, v225, vcc
	v_cndmask_b32_e64 v197, v225, v197, vcc
	v_cvt_pk_bf16_f32 v14, v190, v191
	v_cvt_pk_bf16_f32 v15, v192, v193
	v_cvt_pk_bf16_f32 v16, v194, v195
	v_cvt_pk_bf16_f32 v17, v196, v197
	v_lshlrev_b32_e32 v22, 16, v14
	v_and_b32_e32 v23, 0xffff0000, v14
	v_sub_f32_e32 v190, v190, v22
	v_sub_f32_e32 v191, v191, v23
	v_cvt_pk_bf16_f32 v18, v190, v191
	v_lshlrev_b32_e32 v22, 16, v15
	v_and_b32_e32 v23, 0xffff0000, v15
	v_sub_f32_e32 v192, v192, v22
	v_sub_f32_e32 v193, v193, v23
	v_cvt_pk_bf16_f32 v19, v192, v193
	v_lshlrev_b32_e32 v22, 16, v16
	v_and_b32_e32 v23, 0xffff0000, v16
	v_sub_f32_e32 v194, v194, v22
	v_sub_f32_e32 v195, v195, v23
	v_cvt_pk_bf16_f32 v20, v194, v195
	v_lshlrev_b32_e32 v22, 16, v17
	v_and_b32_e32 v23, 0xffff0000, v17
	v_sub_f32_e32 v196, v196, v22
	v_sub_f32_e32 v197, v197, v23
	v_cvt_pk_bf16_f32 v21, v196, v197
	s_waitcnt lgkmcnt(0)
	v_mfma_f32_16x16x32_bf16 v[10:13], v[198:201], v[14:17], v[10:13]
	v_mfma_f32_16x16x32_bf16 v[6:9], v[206:209], v[14:17], v[6:9]
	v_mfma_f32_16x16x32_bf16 v[2:5], v[214:217], v[14:17], v[2:5]
	v_mfma_f32_16x16x32_bf16 v[10:13], v[198:201], v[18:21], v[10:13]
	v_mfma_f32_16x16x32_bf16 v[6:9], v[206:209], v[18:21], v[6:9]
	v_mfma_f32_16x16x32_bf16 v[2:5], v[214:217], v[18:21], v[2:5]
	v_mfma_f32_16x16x32_bf16 v[10:13], v[202:205], v[14:17], v[10:13]
	v_mfma_f32_16x16x32_bf16 v[6:9], v[210:213], v[14:17], v[6:9]
	v_mfma_f32_16x16x32_bf16 v[2:5], v[218:221], v[14:17], v[2:5]
	s_nop 7
	s_nop 3
	s_and_b64 vcc, exec, s[46:47]
	s_cbranch_vccz .LBB0_50
	s_mul_i32 vcc_lo, s40, 0x1800
	s_ashr_i32 vcc_hi, vcc_lo, 31
	s_lshl_b64 vcc, vcc, 2
	s_add_u32 vcc_lo, s38, vcc_lo
	v_or_b32_e32 v14, s50, v32
	s_addc_u32 vcc_hi, s39, vcc_hi
	v_ashrrev_i32_e32 v15, 31, v14
	v_lshl_add_u64 v[14:15], v[14:15], 2, vcc
	global_load_dword v16, v[14:15], off
	s_branch .LBB0_51
